# v48 + FFN-up conv epilogue: HZ halo stores staged in LDS and issued at the end, conv weights for the second row half re-read from an LDS stash instead of global (no stores ahead of counted vmcnt waits
# speedup vs baseline: 1.0023x; 1.0023x over previous
; #define PG8_LAS __attribute__((address_space(3)))
; __device__ __forceinline__ float rstd2048(const stat_t* rs, int row) { return rsqrtf((float)rs[row] * (STAT_INV / 2048.0f) + NORM_EPS); }
;     __device__ __forceinline__ void operator()(const f32x4 (&acc)[2][2][4][2], const Unit& u, int wr, int wc, int fr_, int fq_) const {
;     ...
;         f32x4 swv[2][2];
; #pragma unroll
;         for (int bj = 0; bj < 2; ++bj)
; #pragma unroll
;             for (int n = 0; n < 2; ++n) swv[bj][n] = *(const f32x4*)(sw + u.pn * BM + bj * HALF + wc * 32 + 8 * fq + 4 * n);
; #pragma unroll
;         for (int ai = 0; ai < 2; ++ai)
; #pragma unroll
;             for (int m = 0; m < 4; ++m) { const float r = rstd2048(rs, rowb + ai * HALF + m) * sx[rowb + ai * HALF + m];
; #pragma unroll
;                 for (int bj = 0; bj < 2; ++bj)
; #pragma unroll
;                     for (int n = 0; n < 2; ++n) { typedef int i32x4 __attribute__((ext_vector_type(4)));
;                         z[ai][bj][m][n] = __builtin_convertvector(__builtin_bit_cast(i32x4, acc[ai][bj][m][n]), f32x4) * (swv[bj][n] * r); } }
;         PG8_LAS f32x4* X4 = (PG8_LAS f32x4*)xch;
;     ...
; #pragma unroll
;         for (int ai = 0; ai < 2; ++ai) {
;             if (fr == 0) {
; #pragma unroll
;                 for (int bj = 0; bj < 2; ++bj)
; #pragma unroll
;                     for (int n = 0; n < 2; ++n) X4[XIDX(wr, ai, 0) + bj * 2 + n] = z[ai][bj][0][n]; }
;             if (fr == 15) {
; #pragma unroll
;                 for (int bj = 0; bj < 2; ++bj)
; #pragma unroll
;                     for (int n = 0; n < 2; ++n) X4[XIDX(wr, ai, 1) + bj * 2 + n] = z[ai][bj][3][n]; }
.LBB0_83:
	s_add_i32 s100, s11, 0xc000
	v_lshlrev_b32_e32 v208, 4, v241
	v_add_u32_e32 v208, s100, v208
	s_lshl_b32 s66, s70, 8
	s_ashr_i32 s67, s66, 31
	v_mov_b32_e32 v174, v240
	v_mov_b32_e32 v175, v241
	s_lshl_b64 s[0:1], s[66:67], 2
	v_readlane_b32 s4, v255, 3
	s_add_u32 s0, s4, s0
	v_readlane_b32 s4, v255, 4
	v_lshlrev_b32_e32 v168, 3, v175
	s_addc_u32 s1, s4, s1
	v_ashrrev_i32_e32 v169, 31, v168
	v_lshl_add_u64 v[34:35], v[168:169], 2, s[0:1]
	s_lshl_b32 s0, s10, 8
	v_readlane_b32 s1, v254, 61
	s_add_i32 s0, s0, s1
	v_lshl_add_u32 v220, v174, 2, s0
	v_readlane_b32 s0, v254, 59
	v_ashrrev_i32_e32 v221, 31, v220
	v_readlane_b32 s1, v254, 60
	global_load_dwordx4 v[18:21], v[34:35], off offset:16
	global_load_dwordx4 v[38:41], v[34:35], off
	global_load_dwordx4 v[22:25], v[34:35], off offset:528
	s_nop 0
	global_load_dwordx4 v[34:37], v[34:35], off offset:512
	v_lshl_add_u64 v[172:173], v[220:221], 3, s[0:1]
	global_load_dwordx4 v[154:157], v[172:173], off offset:16
	global_load_dwordx4 v[164:167], v[172:173], off
	v_readlane_b32 s0, v252, 39
	v_readlane_b32 s1, v252, 40
	v_cvt_f32_i32_e32 v95, v95
	v_cvt_f32_i32_e32 v94, v94
	v_lshl_add_u64 v[170:171], v[220:221], 2, s[0:1]
	global_load_dwordx4 v[158:161], v[170:171], off
	v_cvt_f32_i32_e32 v97, v97
	v_cvt_f32_i32_e32 v96, v96
	v_cvt_f32_i32_e32 v59, v59
	v_cvt_f32_i32_e32 v58, v58
	v_cvt_f32_i32_e32 v61, v61
	v_cvt_f32_i32_e32 v60, v60
	v_cvt_f32_i32_e32 v79, v79
	v_cvt_f32_i32_e32 v78, v78
	v_cvt_f32_i32_e32 v81, v81
	v_cvt_f32_i32_e32 v80, v80
	v_cvt_f32_i32_e32 v63, v63
	v_cvt_f32_i32_e32 v62, v62
	v_cvt_f32_i32_e32 v65, v65
	v_cvt_f32_i32_e32 v64, v64
	v_lshlrev_b32_e32 v205, 6, v175
	v_cmp_lt_i32_e64 s[12:13], 14, v174
	s_mov_b64 s[6:7], 0
	s_waitcnt vmcnt(0)
	v_ffbh_u32_e32 v130, v165
	v_min_u32_e32 v132, 32, v130
	v_lshlrev_b64 v[130:131], v132, v[164:165]
	v_min_u32_e32 v130, 1, v130
	v_or_b32_e32 v130, v131, v130
	v_cvt_f32_u32_e32 v130, v130
	v_sub_u32_e32 v131, 32, v132
	v_ldexp_f32 v130, v130, v131
	v_fmamk_f32 v169, v130, 0x2e000000, v204
	v_ffbh_u32_e32 v130, v157
	v_min_u32_e32 v132, 32, v130
	v_lshlrev_b64 v[130:131], v132, v[156:157]
	v_min_u32_e32 v130, 1, v130
	v_or_b32_e32 v130, v131, v130
	v_cvt_f32_u32_e32 v130, v130
	v_sub_u32_e32 v131, 32, v132
	v_cmp_gt_f32_e32 vcc, s17, v169
	v_ldexp_f32 v130, v130, v131
	v_fmamk_f32 v130, v130, 0x2e000000, v204
	v_cmp_gt_f32_e64 s[0:1], s17, v130
	v_mul_f32_e32 v131, 0x4b800000, v130
	s_nop 0
	v_cndmask_b32_e64 v130, v130, v131, s[0:1]
	v_rsq_f32_e32 v130, v130
	s_nop 0
	v_mul_f32_e32 v131, 0x45800000, v130
	v_cndmask_b32_e64 v130, v130, v131, s[0:1]
	v_mul_f32_e32 v156, v161, v130
	v_pk_mul_f32 v[130:131], v[38:39], v[156:157] op_sel_hi:[1,0]
	v_pk_mul_f32 v[132:133], v[40:41], v[156:157] op_sel_hi:[1,0]
	v_pk_mul_f32 v[130:131], v[130:131], v[94:95]
	v_pk_mul_f32 v[132:133], v[132:133], v[96:97]
	v_pk_mul_f32 v[94:95], v[18:19], v[156:157] op_sel_hi:[1,0]
	v_pk_mul_f32 v[96:97], v[20:21], v[156:157] op_sel_hi:[1,0]
	v_pk_mul_f32 v[58:59], v[94:95], v[58:59]
	v_pk_mul_f32 v[60:61], v[96:97], v[60:61]
	v_pk_mul_f32 v[94:95], v[34:35], v[156:157] op_sel_hi:[1,0]
	v_pk_mul_f32 v[96:97], v[36:37], v[156:157] op_sel_hi:[1,0]
	v_pk_mul_f32 v[134:135], v[94:95], v[78:79]
	v_pk_mul_f32 v[136:137], v[96:97], v[80:81]
	v_pk_mul_f32 v[78:79], v[22:23], v[156:157] op_sel_hi:[1,0]
	v_pk_mul_f32 v[80:81], v[24:25], v[156:157] op_sel_hi:[1,0]
	v_pk_mul_f32 v[62:63], v[78:79], v[62:63]
	v_pk_mul_f32 v[64:65], v[80:81], v[64:65]
	global_load_dwordx4 v[162:165], v[172:173], off offset:1040
	global_load_dwordx4 v[78:81], v[172:173], off offset:1024
	s_waitcnt vmcnt(0)
	v_ffbh_u32_e32 v94, v79
	v_min_u32_e32 v94, 32, v94
	v_lshlrev_b64 v[78:79], v94, v[78:79]
	v_min_u32_e32 v78, 1, v78
	v_or_b32_e32 v78, v79, v78
	v_sub_u32_e32 v79, 32, v94
	global_load_dwordx4 v[94:97], v[170:171], off offset:512
	v_cvt_f32_u32_e32 v78, v78
	v_ldexp_f32 v78, v78, v79
	v_ffbh_u32_e32 v79, v165
	v_min_u32_e32 v79, 32, v79
	v_lshlrev_b64 v[156:157], v79, v[164:165]
	v_min_u32_e32 v156, 1, v156
	v_or_b32_e32 v156, v157, v156
	v_cvt_f32_u32_e32 v156, v156
	v_sub_u32_e32 v79, 32, v79
	v_fmamk_f32 v78, v78, 0x2e000000, v204
	v_cmp_gt_f32_e64 s[0:1], s17, v78
	v_ldexp_f32 v79, v156, v79
	v_fmamk_f32 v79, v79, 0x2e000000, v204
	v_cmp_gt_f32_e64 s[8:9], s17, v79
	s_and_saveexec_b64 s[82:83], s[12:13]
	s_xor_b64 s[96:97], exec, s[82:83]
	s_cbranch_execz .LBB0_87
	v_cmp_eq_u32_e64 s[12:13], 15, v174
	s_and_saveexec_b64 s[82:83], s[12:13]
	s_cbranch_execz .LBB0_86
	v_readlane_b32 s4, v255, 6
	s_mov_b64 s[6:7], exec
	s_nop 0
	v_add_u32_e32 v156, s4, v205
	ds_write_b128 v156, v[130:133] offset:256
	ds_write_b128 v156, v[58:61] offset:272
	ds_write_b128 v156, v[134:137] offset:288
	ds_write_b128 v156, v[62:65] offset:304

; #define PG8_LAS __attribute__((address_space(3)))
; __device__ __forceinline__ float rstd2048(const stat_t* rs, int row) { return rsqrtf((float)rs[row] * (STAT_INV / 2048.0f) + NORM_EPS); }
;     __device__ __forceinline__ void operator()(const f32x4 (&acc)[2][2][4][2], const Unit& u, int wr, int wc, int fr_, int fq_) const {
;     ...
;             for (int m = 0; m < 4; ++m) { const float r = rstd2048(rs, rowb + ai * HALF + m) * sx[rowb + ai * HALF + m];
; #pragma unroll
;                 for (int bj = 0; bj < 2; ++bj)
; #pragma unroll
;                     for (int n = 0; n < 2; ++n) { typedef int i32x4 __attribute__((ext_vector_type(4)));
;                         z[ai][bj][m][n] = __builtin_convertvector(__builtin_bit_cast(i32x4, acc[ai][bj][m][n]), f32x4) * (swv[bj][n] * r); } }
;         PG8_LAS f32x4* X4 = (PG8_LAS f32x4*)xch;
;     ...
; #pragma unroll
;         for (int ai = 0; ai < 2; ++ai) {
;             if (fr == 0) {
; #pragma unroll
;                 for (int bj = 0; bj < 2; ++bj)
; #pragma unroll
;                     for (int n = 0; n < 2; ++n) X4[XIDX(wr, ai, 0) + bj * 2 + n] = z[ai][bj][0][n]; }
;             if (fr == 15) {
; #pragma unroll
;                 for (int bj = 0; bj < 2; ++bj)
; #pragma unroll
;                     for (int n = 0; n < 2; ++n) X4[XIDX(wr, ai, 1) + bj * 2 + n] = z[ai][bj][3][n]; }
;         }
;         {   const int hcol = u.pn * BM + wc * 32 + 8 * fq;
;             if (wr == 0 && fr == 0) {
; #pragma unroll
;                 for (int m = 0; m < 2; ++m)
; #pragma unroll
;                     for (int bj = 0; bj < 2; ++bj)
; #pragma unroll
;                         for (int n = 0; n < 2; ++n) *(f32x4*)(HZ + (size_t)(u.pm * 4 + m) * NZ_ + hcol + bj * HALF + 4 * n) = z[0][bj][m][n]; }
;             if (wr == 1 && fr == 15) {
; #pragma unroll
;                 for (int m = 2; m < 4; ++m)
; #pragma unroll
;                     for (int bj = 0; bj < 2; ++bj)
; #pragma unroll
;                         for (int n = 0; n < 2; ++n) *(f32x4*)(HZ + (size_t)(u.pm * 4 + m) * NZ_ + hcol + bj * HALF + 4 * n) = z[1][bj][m][n]; }
.LBB0_97:
	s_or_b64 exec, exec, s[0:1]
	v_ffbh_u32_e32 v78, v167
	v_min_u32_e32 v94, 32, v78
	v_lshlrev_b64 v[78:79], v94, v[166:167]
	v_min_u32_e32 v78, 1, v78
	v_or_b32_e32 v78, v79, v78
	v_cvt_f32_u32_e32 v78, v78
	v_sub_u32_e32 v94, 32, v94
	v_cvt_f32_i32_e32 v79, v119
	v_cvt_f32_i32_e32 v119, v121
	v_ldexp_f32 v78, v78, v94
	v_fmamk_f32 v78, v78, 0x2e000000, v204
	v_mul_f32_e32 v94, 0x4b800000, v78
	v_cmp_gt_f32_e32 vcc, s17, v78
	v_cvt_f32_i32_e32 v113, v113
	v_cvt_f32_i32_e32 v112, v112
	v_cndmask_b32_e32 v78, v78, v94, vcc
	v_rsq_f32_e32 v94, v78
	v_cvt_f32_i32_e32 v78, v118
	v_cvt_f32_i32_e32 v118, v120
	v_cvt_f32_i32_e32 v105, v105
	v_mul_f32_e32 v97, 0x45800000, v94
	v_cndmask_b32_e32 v94, v94, v97, vcc
	v_mul_f32_e32 v94, v159, v94
	v_pk_mul_f32 v[156:157], v[38:39], v[94:95] op_sel_hi:[1,0]
	v_pk_mul_f32 v[120:121], v[40:41], v[94:95] op_sel_hi:[1,0]
	v_cvt_f32_i32_e32 v104, v104
	v_pk_mul_f32 v[120:121], v[120:121], v[118:119]
	v_pk_mul_f32 v[118:119], v[156:157], v[78:79]
	v_cvt_f32_i32_e32 v79, v111
	v_cvt_f32_i32_e32 v78, v110
	v_pk_mul_f32 v[110:111], v[18:19], v[94:95] op_sel_hi:[1,0]
	v_pk_mul_f32 v[156:157], v[20:21], v[94:95] op_sel_hi:[1,0]
	v_cvt_f32_i32_e32 v101, v101
	v_pk_mul_f32 v[110:111], v[110:111], v[78:79]
	v_cvt_f32_i32_e32 v79, v103
	v_cvt_f32_i32_e32 v78, v102
	v_pk_mul_f32 v[112:113], v[156:157], v[112:113]
	v_pk_mul_f32 v[102:103], v[34:35], v[94:95] op_sel_hi:[1,0]
	v_pk_mul_f32 v[156:157], v[36:37], v[94:95] op_sel_hi:[1,0]
	v_cvt_f32_i32_e32 v100, v100
	v_pk_mul_f32 v[158:159], v[156:157], v[104:105]
	v_pk_mul_f32 v[156:157], v[102:103], v[78:79]
	v_cvt_f32_i32_e32 v79, v99
	v_cvt_f32_i32_e32 v78, v98
	v_pk_mul_f32 v[98:99], v[22:23], v[94:95] op_sel_hi:[1,0]
	s_or_b32 s0, s66, s36
	v_pk_mul_f32 v[102:103], v[24:25], v[94:95] op_sel_hi:[1,0]
	v_pk_mul_f32 v[98:99], v[98:99], v[78:79]
	v_add_u32_e32 v78, s0, v168
	v_mov_b32_e32 v209, v78
	v_readlane_b32 s0, v254, 58
	v_pk_mul_f32 v[100:101], v[102:103], v[100:101]
	s_nop 0
	v_or_b32_e32 v79, s0, v174
	v_cmp_eq_u32_e32 vcc, 0, v79
	v_ashrrev_i32_e32 v79, 31, v78
	s_and_saveexec_b64 s[0:1], vcc
	s_cbranch_execz .LBB0_99
	s_lshl_b32 s4, s10, 2
	s_mul_i32 s5, s10, 0x2c000
	v_readlane_b32 s8, v252, 43
	s_mul_hi_i32 s7, s4, 0xb000
	v_readlane_b32 s9, v252, 44
	s_add_u32 s6, s8, s5
	s_addc_u32 s7, s9, s7
	s_or_b32 s4, s4, 1
	v_lshlrev_b64 v[102:103], 2, v[78:79]
	s_mul_hi_i32 s5, s4, 0xb000
	s_mul_i32 s4, s4, 0xb000
	v_lshl_add_u64 v[104:105], s[6:7], 0, v[102:103]
	s_add_u32 s6, s8, s4
	s_addc_u32 s7, s9, s5
	v_lshl_add_u64 v[102:103], s[6:7], 0, v[102:103]
	ds_write_b128 v208, v[150:153] offset:8192
	ds_write_b128 v208, v[146:149] offset:8256
	ds_write_b128 v208, v[142:145] offset:8320
	ds_write_b128 v208, v[138:141] offset:8384
	ds_write_b128 v208, v[118:121] offset:8448
	ds_write_b128 v208, v[110:113] offset:8512
	ds_write_b128 v208, v[156:159] offset:8576
	ds_write_b128 v208, v[98:101] offset:8640
.LBB0_99:
	s_or_b64 exec, exec, s[0:1]
	v_ffbh_u32_e32 v94, v163
	v_min_u32_e32 v94, 32, v94
	v_lshlrev_b64 v[102:103], v94, v[162:163]
	v_min_u32_e32 v97, 1, v102
	v_or_b32_e32 v97, v103, v97
	v_cvt_f32_u32_e32 v97, v97
	v_sub_u32_e32 v94, 32, v94
	v_cvt_f32_i32_e32 v91, v91
	v_cvt_f32_i32_e32 v90, v90
	v_ldexp_f32 v94, v97, v94
	v_fmamk_f32 v94, v94, 0x2e000000, v204
	v_mul_f32_e32 v97, 0x4b800000, v94
	v_cmp_gt_f32_e32 vcc, s17, v94
	v_cvt_f32_i32_e32 v93, v93
	v_cvt_f32_i32_e32 v92, v92
	v_cndmask_b32_e32 v94, v94, v97, vcc
	v_rsq_f32_e32 v94, v94
	v_cvt_f32_i32_e32 v87, v87
	v_cvt_f32_i32_e32 v89, v89
	v_cvt_f32_i32_e32 v88, v88
	v_mul_f32_e32 v97, 0x45800000, v94
	v_cndmask_b32_e32 v94, v94, v97, vcc
	v_cvt_f32_i32_e32 v86, v86
	v_mul_f32_e32 v94, v96, v94
	v_cvt_f32_i32_e32 v83, v83
	v_cvt_f32_i32_e32 v85, v85
	v_cvt_f32_i32_e32 v84, v84
	v_cvt_f32_i32_e32 v82, v82
	v_pk_mul_f32 v[96:97], v[38:39], v[94:95] op_sel_hi:[1,0]
	v_pk_mul_f32 v[102:103], v[40:41], v[94:95] op_sel_hi:[1,0]
	v_cvt_f32_i32_e32 v75, v75
	v_cvt_f32_i32_e32 v77, v77
	v_cvt_f32_i32_e32 v76, v76
	v_cvt_f32_i32_e32 v74, v74
	v_pk_mul_f32 v[92:93], v[102:103], v[92:93]
	v_pk_mul_f32 v[90:91], v[96:97], v[90:91]
	v_pk_mul_f32 v[96:97], v[18:19], v[94:95] op_sel_hi:[1,0]
	v_pk_mul_f32 v[102:103], v[20:21], v[94:95] op_sel_hi:[1,0]
	v_pk_mul_f32 v[86:87], v[96:97], v[86:87]
	v_pk_mul_f32 v[88:89], v[102:103], v[88:89]
	v_pk_mul_f32 v[96:97], v[34:35], v[94:95] op_sel_hi:[1,0]
	v_pk_mul_f32 v[102:103], v[36:37], v[94:95] op_sel_hi:[1,0]
	v_pk_mul_f32 v[82:83], v[96:97], v[82:83]
	v_pk_mul_f32 v[84:85], v[102:103], v[84:85]
	v_pk_mul_f32 v[96:97], v[22:23], v[94:95] op_sel_hi:[1,0]
	v_pk_mul_f32 v[102:103], v[24:25], v[94:95] op_sel_hi:[1,0]
	v_cmp_eq_u32_e32 vcc, 15, v174
	v_pk_mul_f32 v[76:77], v[102:103], v[76:77]
	v_pk_mul_f32 v[74:75], v[96:97], v[74:75]
	s_and_b64 s[6:7], s[46:47], vcc
	s_and_saveexec_b64 s[0:1], s[6:7]
	s_mov_b32 s12, s38
	s_cbranch_execz .LBB0_101
	s_lshl_b32 s4, s10, 2
	s_or_b32 s5, s4, 2
	s_mul_hi_i32 s7, s5, 0xb000
	s_mul_i32 s5, s5, 0xb000
	v_readlane_b32 s8, v252, 43
	v_readlane_b32 s9, v252, 44
	s_add_u32 s6, s8, s5
	s_addc_u32 s7, s9, s7
	s_or_b32 s4, s4, 3
	v_lshlrev_b64 v[78:79], 2, v[78:79]
	s_mul_hi_i32 s5, s4, 0xb000
	s_mul_i32 s4, s4, 0xb000
	v_lshl_add_u64 v[96:97], s[6:7], 0, v[78:79]
	s_add_u32 s6, s8, s4
	s_addc_u32 s7, s9, s5
	v_lshl_add_u64 v[78:79], s[6:7], 0, v[78:79]
	ds_write_b128 v208, v[90:93] offset:8192
	ds_write_b128 v208, v[86:89] offset:8256
	ds_write_b128 v208, v[82:85] offset:8320
	ds_write_b128 v208, v[74:77] offset:8384
	ds_write_b128 v208, v[126:129] offset:8448
	ds_write_b128 v208, v[66:69] offset:8512
	ds_write_b128 v208, v[122:125] offset:8576
	ds_write_b128 v208, v[70:73] offset:8640

;     __device__ __forceinline__ void operator()(const f32x4 (&acc)[2][2][4][2], const Unit& u, int wr, int wc, int fr_, int fq_) const {
;     ...
;             for (int n = 0; n < 2; ++n) {
;                 const int ch = ch0 + 4 * n;
;                 const f32x4 w0g = *(const f32x4*)(cw + ch), w1g = *(const f32x4*)(cw + NZ_ + ch), w2g = *(const f32x4*)(cw + 2 * NZ_ + ch), bg = *(const f32x4*)(cb + ch);
;                 const f32x4 w0u = *(const f32x4*)(cw + DFF_ + ch), w1u = *(const f32x4*)(cw + NZ_ + DFF_ + ch), w2u = *(const f32x4*)(cw + 2 * NZ_ + DFF_ + ch), bu = *(const f32x4*)(cb + DFF_ + ch);
;                 f32x4 pBg = zero4, pBu = zero4, nBg = zero4, nBu = zero4;
;                 if (wr == 1) { pBg = X4[XIDX(0, ai, 1) + n]; pBu = X4[XIDX(0, ai, 1) + 2 + n]; }
;                 else if (ai == 1) { pBg = X4[XIDX(1, 0, 1) + n]; pBu = X4[XIDX(1, 0, 1) + 2 + n]; }
;                 if (wr == 0) { nBg = X4[XIDX(1, ai, 0) + n]; nBu = X4[XIDX(1, ai, 0) + 2 + n]; }
;                 else if (ai == 0) { nBg = X4[XIDX(0, 1, 0) + n]; nBu = X4[XIDX(0, 1, 0) + 2 + n]; }
;                 float o[4][4];
; #pragma unroll
;                 for (int h = 0; h < 2; ++h) {
;                     typedef float f32x2 __attribute__((ext_vector_type(2)));
;     ...
;                     const f32x2 g0 = PAIR(z[ai][0][0][n]), g1 = PAIR(z[ai][0][1][n]), g2 = PAIR(z[ai][0][2][n]), g3 = PAIR(z[ai][0][3][n]);
;                     const f32x2 u0 = PAIR(z[ai][1][0][n]), u1 = PAIR(z[ai][1][1][n]), u2 = PAIR(z[ai][1][2][n]), u3 = PAIR(z[ai][1][3][n]);
;                     const f32x2 pBg2 = PAIR(pBg), nBg2 = PAIR(nBg), pBu2 = PAIR(pBu), nBu2 = PAIR(nBu);
;                     f32x2 pg, ng, pu, nu;
;                     pg.x = dpp_shr1(pBg2.x, g3.x); pg.y = dpp_shr1(pBg2.y, g3.y); ng.x = dpp_shl1(nBg2.x, g0.x); ng.y = dpp_shl1(nBg2.y, g0.y);
;                     pu.x = dpp_shr1(pBu2.x, u3.x); pu.y = dpp_shr1(pBu2.y, u3.y); nu.x = dpp_shl1(nBu2.x, u0.x); nu.y = dpp_shl1(nBu2.y, u0.y);
;                     const f32x2 A0 = PAIR(w0g), A1 = PAIR(w1g), A2 = PAIR(w2g), AB = PAIR(bg), C0 = PAIR(w0u), C1 = PAIR(w1u), C2 = PAIR(w2u), CB = PAIR(bu);
;                     f32x2 G[4], U[4];
;                     G[0] = A0 * pg + (A1 * g0 + (A2 * g1 + AB)); G[1] = A0 * g0 + (A1 * g1 + (A2 * g2 + AB)); G[2] = A0 * g1 + (A1 * g2 + (A2 * g3 + AB)); G[3] = A0 * g2 + (A1 * g3 + (A2 * ng + AB));
.LBB0_103:
	v_ffbh_u32_e32 v96, v155
	v_min_u32_e32 v103, 32, v96
	v_lshlrev_b64 v[96:97], v103, v[154:155]
	v_min_u32_e32 v96, 1, v96
	v_or_b32_e32 v96, v97, v96
	v_cvt_f32_u32_e32 v96, v96
	v_sub_u32_e32 v97, 32, v103
	v_cvt_f32_i32_e32 v43, v43
	v_cvt_f32_i32_e32 v42, v42
	v_ldexp_f32 v96, v96, v97
	v_fmamk_f32 v96, v96, 0x2e000000, v204
	v_cmp_gt_f32_e32 vcc, s17, v96
	v_mul_f32_e32 v97, 0x4b800000, v96
	v_cvt_f32_i32_e32 v45, v45
	v_cndmask_b32_e32 v96, v96, v97, vcc
	v_rsq_f32_e32 v96, v96
	v_cvt_f32_i32_e32 v44, v44
	v_readlane_b32 s0, v254, 63
	s_waitcnt vmcnt(4)
	v_pk_fma_f32 v[154:155], v[118:119], v[182:183], v[190:191]
	v_mul_f32_e32 v97, 0x45800000, v96
	v_cndmask_b32_e32 v96, v96, v97, vcc
	v_mul_f32_e32 v238, v160, v96
	v_cvt_f32_i32_e32 v97, v55
	v_cvt_f32_i32_e32 v96, v54
	v_cvt_f32_i32_e32 v55, v57
	v_cvt_f32_i32_e32 v54, v56
	v_pk_mul_f32 v[104:105], v[40:41], v[238:239] op_sel_hi:[1,0]
	v_pk_mul_f32 v[56:57], v[38:39], v[238:239] op_sel_hi:[1,0]
	v_pk_fma_f32 v[154:155], v[150:151], v[174:175], v[154:155]
	v_pk_mul_f32 v[54:55], v[104:105], v[54:55]
	v_pk_mul_f32 v[104:105], v[34:35], v[238:239] op_sel_hi:[1,0]
	v_pk_mul_f32 v[96:97], v[56:57], v[96:97]
	v_pk_mul_f32 v[56:57], v[36:37], v[238:239] op_sel_hi:[1,0]
	v_pk_mul_f32 v[104:105], v[104:105], v[42:43]
	v_add_u32_e32 v42, s0, v94
	v_pk_mul_f32 v[56:57], v[56:57], v[44:45]
	ds_read_b128 v[42:45], v42
	v_readlane_b32 s0, v254, 62
	v_pk_fma_f32 v[160:161], v[96:97], v[182:183], v[190:191]
	s_waitcnt lgkmcnt(2)
	v_mov_b32_dpp v198, v130 row_shr:1 row_mask:0xf bank_mask:0xf
	v_add_u32_e32 v103, s0, v94
	ds_read_b128 v[244:247], v103
	s_waitcnt lgkmcnt(1)
	v_mov_b32_dpp v42, v150 row_shl:1 row_mask:0xf bank_mask:0xf
	v_mov_b32_dpp v43, v151 row_shl:1 row_mask:0xf bank_mask:0xf
	v_pk_fma_f32 v[160:161], v[118:119], v[174:175], v[160:161]
	v_pk_fma_f32 v[42:43], v[182:183], v[42:43], v[190:191]
	v_pk_fma_f32 v[150:151], v[150:151], v[166:167], v[160:161]
	v_pk_fma_f32 v[160:161], v[130:131], v[182:183], v[190:191]
	v_pk_fma_f32 v[42:43], v[130:131], v[174:175], v[42:43]
	v_mov_b32_dpp v199, v131 row_shr:1 row_mask:0xf bank_mask:0xf
	v_pk_fma_f32 v[160:161], v[96:97], v[174:175], v[160:161]
	v_pk_fma_f32 v[130:131], v[96:97], v[166:167], v[42:43]
	s_waitcnt vmcnt(0)
	s_mov_b64 s[98:99], exec
	s_mov_b32 s100, 0x10001
	s_mov_b32 s101, 0x10001
	s_mov_b64 exec, s[100:101]
	ds_write_b128 v208, v[166:169] offset:0
	ds_write_b128 v208, v[174:177] offset:64
	ds_write_b128 v208, v[182:185] offset:128
	ds_write_b128 v208, v[190:193] offset:192
	ds_write_b128 v208, v[162:165] offset:256
	ds_write_b128 v208, v[170:173] offset:320
	ds_write_b128 v208, v[178:181] offset:384
	ds_write_b128 v208, v[186:189] offset:448
	s_mov_b64 exec, s[98:99]
	v_pk_fma_f32 v[96:97], v[104:105], v[178:179], v[186:187]
	v_pk_fma_f32 v[42:43], v[156:157], v[178:179], v[186:187]
	v_pk_fma_f32 v[96:97], v[156:157], v[170:171], v[96:97]
	s_waitcnt lgkmcnt(0)
	v_mov_b32_dpp v244, v142 row_shl:1 row_mask:0xf bank_mask:0xf
	v_mov_b32_dpp v245, v143 row_shl:1 row_mask:0xf bank_mask:0xf
	v_pk_fma_f32 v[42:43], v[142:143], v[170:171], v[42:43]
	v_pk_fma_f32 v[96:97], v[142:143], v[162:163], v[96:97]
	v_pk_fma_f32 v[142:143], v[134:135], v[178:179], v[186:187]
	v_mov_b32_dpp v194, v134 row_shr:1 row_mask:0xf bank_mask:0xf
	v_pk_fma_f32 v[142:143], v[104:105], v[170:171], v[142:143]
	v_mov_b32_dpp v195, v135 row_shr:1 row_mask:0xf bank_mask:0xf
	v_pk_fma_f32 v[142:143], v[156:157], v[162:163], v[142:143]
	v_pk_fma_f32 v[156:157], v[178:179], v[244:245], v[186:187]
	v_pk_fma_f32 v[154:155], v[166:167], v[198:199], v[154:155]
	v_pk_fma_f32 v[134:135], v[134:135], v[170:171], v[156:157]
	s_mov_b32 s0, 0xbfb8aa3b
	v_pk_fma_f32 v[134:135], v[104:105], v[162:163], v[134:135]
	v_pk_mul_f32 v[104:105], v[154:155], s[0:1] op_sel_hi:[1,0]
	v_pk_fma_f32 v[42:43], v[162:163], v[194:195], v[42:43]
	v_exp_f32_e32 v104, v104
	v_exp_f32_e32 v105, v105
	v_pk_mul_f32 v[42:43], v[154:155], v[42:43]
	v_pk_fma_f32 v[118:119], v[118:119], v[166:167], v[160:161]
	v_pk_mul_f32 v[96:97], v[150:151], v[96:97]
	v_pk_add_f32 v[104:105], v[104:105], 1.0 op_sel_hi:[1,0]
	v_mov_b32_dpp v44, v152 row_shl:1 row_mask:0xf bank_mask:0xf
	v_rcp_f32_e32 v104, v104
	v_rcp_f32_e32 v105, v105
	v_mov_b32_dpp v45, v153 row_shl:1 row_mask:0xf bank_mask:0xf
	v_pk_fma_f32 v[44:45], v[184:185], v[44:45], v[192:193]
	v_mov_b32_dpp v200, v132 row_shr:1 row_mask:0xf bank_mask:0xf
	v_pk_mul_f32 v[42:43], v[42:43], v[104:105]
	v_pk_mul_f32 v[104:105], v[150:151], s[0:1] op_sel_hi:[1,0]
	v_mov_b32_dpp v201, v133 row_shr:1 row_mask:0xf bank_mask:0xf
	v_exp_f32_e32 v104, v104
	v_exp_f32_e32 v105, v105
	v_pk_fma_f32 v[44:45], v[132:133], v[176:177], v[44:45]
	v_mov_b32_dpp v246, v144 row_shl:1 row_mask:0xf bank_mask:0xf
	v_mov_b32_dpp v247, v145 row_shl:1 row_mask:0xf bank_mask:0xf
	v_pk_add_f32 v[104:105], v[104:105], 1.0 op_sel_hi:[1,0]
	v_pk_fma_f32 v[44:45], v[54:55], v[168:169], v[44:45]
	v_rcp_f32_e32 v104, v104
	v_rcp_f32_e32 v105, v105
	v_mov_b32_dpp v196, v136 row_shr:1 row_mask:0xf bank_mask:0xf
	v_mov_b32_dpp v197, v137 row_shr:1 row_mask:0xf bank_mask:0xf
	s_and_b64 vcc, exec, s[8:9]
	v_pk_mul_f32 v[96:97], v[96:97], v[104:105]
	v_pk_mul_f32 v[104:105], v[118:119], s[0:1] op_sel_hi:[1,0]
	v_pk_mul_f32 v[118:119], v[118:119], v[142:143]
	v_exp_f32_e32 v104, v104
	v_exp_f32_e32 v105, v105
	v_pk_fma_f32 v[142:143], v[132:133], v[184:185], v[192:193]
	v_pk_fma_f32 v[132:133], v[56:57], v[180:181], v[188:189]
	v_pk_fma_f32 v[142:143], v[54:55], v[176:177], v[142:143]
	v_pk_add_f32 v[104:105], v[104:105], 1.0 op_sel_hi:[1,0]
	v_pk_fma_f32 v[132:133], v[158:159], v[172:173], v[132:133]
; #define PAIR(v) (h == 0 ? __builtin_shufflevector(v, v, 0, 1) : __builtin_shufflevector(v, v, 2, 3))
;     __device__ __forceinline__ void operator()(const f32x4 (&acc)[2][2][4][2], const Unit& u, int wr, int wc, int fr_, int fq_) const {
;     ...
;             for (int n = 0; n < 2; ++n) {
;                 const int ch = ch0 + 4 * n;
;     ...
;                     const f32x2 g0 = PAIR(z[ai][0][0][n]), g1 = PAIR(z[ai][0][1][n]), g2 = PAIR(z[ai][0][2][n]), g3 = PAIR(z[ai][0][3][n]);
;                     const f32x2 u0 = PAIR(z[ai][1][0][n]), u1 = PAIR(z[ai][1][1][n]), u2 = PAIR(z[ai][1][2][n]), u3 = PAIR(z[ai][1][3][n]);
;                     const f32x2 pBg2 = PAIR(pBg), nBg2 = PAIR(nBg), pBu2 = PAIR(pBu), nBu2 = PAIR(nBu);
;                     f32x2 pg, ng, pu, nu;
;                     pg.x = dpp_shr1(pBg2.x, g3.x); pg.y = dpp_shr1(pBg2.y, g3.y); ng.x = dpp_shl1(nBg2.x, g0.x); ng.y = dpp_shl1(nBg2.y, g0.y);
;                     pu.x = dpp_shr1(pBu2.x, u3.x); pu.y = dpp_shr1(pBu2.y, u3.y); nu.x = dpp_shl1(nBu2.x, u0.x); nu.y = dpp_shl1(nBu2.y, u0.y);
;                     const f32x2 A0 = PAIR(w0g), A1 = PAIR(w1g), A2 = PAIR(w2g), AB = PAIR(bg), C0 = PAIR(w0u), C1 = PAIR(w1u), C2 = PAIR(w2u), CB = PAIR(bu);
;                     f32x2 G[4], U[4];
;                     G[0] = A0 * pg + (A1 * g0 + (A2 * g1 + AB)); G[1] = A0 * g0 + (A1 * g1 + (A2 * g2 + AB)); G[2] = A0 * g1 + (A1 * g2 + (A2 * g3 + AB)); G[3] = A0 * g2 + (A1 * g3 + (A2 * ng + AB));
;                     U[0] = C0 * pu + (C1 * u0 + (C2 * u1 + CB)); U[1] = C0 * u0 + (C1 * u1 + (C2 * u2 + CB)); U[2] = C0 * u1 + (C1 * u2 + (C2 * u3 + CB)); U[3] = C0 * u2 + (C1 * u3 + (C2 * nu + CB));
; #pragma unroll
;                     for (int m = 0; m < 4; ++m) {
;                         const f32x2 t = G[m] * (-1.4426950408889634f);
;                         f32x2 e; e.x = __builtin_amdgcn_exp2f(t.x); e.y = __builtin_amdgcn_exp2f(t.y);
;                         const f32x2 d = e + 1.0f;
;                         f32x2 r; r.x = __builtin_amdgcn_rcpf(d.x); r.y = __builtin_amdgcn_rcpf(d.y);
;                         const f32x2 q = (G[m] * U[m]) * r;
;                         o[m][2 * h] = q.x; o[m][2 * h + 1] = q.y;
;                     }
;     ...
;                 }
; #pragma unroll
;                 for (int m = 0; m < 4; ++m) { ow[m][2 * n] = cvt_pk_bf16(o[m][0], o[m][1]); ow[m][2 * n + 1] = cvt_pk_bf16(o[m][2], o[m][3]); }
	v_rcp_f32_e32 v104, v104
	v_rcp_f32_e32 v105, v105
	v_pk_fma_f32 v[132:133], v[144:145], v[164:165], v[132:133]
	v_mov_b32_e32 v103, 0
	v_mov_b32_e32 v170, 0
	v_pk_mul_f32 v[104:105], v[118:119], v[104:105]
	v_pk_mul_f32 v[118:119], v[130:131], s[0:1] op_sel_hi:[1,0]
	v_pk_mul_f32 v[130:131], v[130:131], v[134:135]
	v_exp_f32_e32 v118, v118
	v_exp_f32_e32 v119, v119
	v_pk_fma_f32 v[134:135], v[54:55], v[184:185], v[192:193]
	v_pk_fma_f32 v[54:55], v[158:159], v[180:181], v[188:189]
	v_pk_fma_f32 v[134:135], v[120:121], v[176:177], v[134:135]
	v_pk_add_f32 v[118:119], v[118:119], 1.0 op_sel_hi:[1,0]
	v_pk_fma_f32 v[54:55], v[144:145], v[172:173], v[54:55]
	v_rcp_f32_e32 v118, v118
	v_rcp_f32_e32 v119, v119
	v_pk_fma_f32 v[144:145], v[180:181], v[246:247], v[188:189]
	v_pk_fma_f32 v[134:135], v[152:153], v[168:169], v[134:135]
	v_pk_fma_f32 v[54:55], v[164:165], v[196:197], v[54:55]
	v_pk_mul_f32 v[130:131], v[130:131], v[118:119]
	v_pk_fma_f32 v[118:119], v[120:121], v[184:185], v[192:193]
	v_pk_fma_f32 v[120:121], v[120:121], v[168:169], v[142:143]
	v_pk_fma_f32 v[118:119], v[152:153], v[176:177], v[118:119]
	v_pk_fma_f32 v[142:143], v[136:137], v[180:181], v[188:189]
	v_pk_fma_f32 v[118:119], v[168:169], v[200:201], v[118:119]
	v_pk_fma_f32 v[136:137], v[136:137], v[172:173], v[144:145]
	v_pk_fma_f32 v[142:143], v[56:57], v[172:173], v[142:143]
	v_pk_fma_f32 v[56:57], v[56:57], v[164:165], v[136:137]
	v_pk_mul_f32 v[136:137], v[118:119], s[0:1] op_sel_hi:[1,0]
	v_pk_mul_f32 v[54:55], v[118:119], v[54:55]
	v_pk_mul_f32 v[118:119], v[134:135], s[0:1] op_sel_hi:[1,0]
	v_pk_mul_f32 v[132:133], v[134:135], v[132:133]
	v_exp_f32_e32 v118, v118
	v_exp_f32_e32 v119, v119
	v_pk_fma_f32 v[142:143], v[158:159], v[164:165], v[142:143]
	v_exp_f32_e32 v136, v136
	v_exp_f32_e32 v137, v137
	v_pk_add_f32 v[118:119], v[118:119], 1.0 op_sel_hi:[1,0]
	v_mov_b32_e32 v171, 0
	v_rcp_f32_e32 v118, v118
	v_rcp_f32_e32 v119, v119
	v_pk_add_f32 v[136:137], v[136:137], 1.0 op_sel_hi:[1,0]
	v_mov_b32_e32 v172, 0
	v_rcp_f32_e32 v136, v136
	v_pk_mul_f32 v[132:133], v[132:133], v[118:119]
	v_pk_mul_f32 v[118:119], v[120:121], s[0:1] op_sel_hi:[1,0]
	v_pk_mul_f32 v[120:121], v[120:121], v[142:143]
	v_exp_f32_e32 v118, v118
	v_exp_f32_e32 v119, v119
	v_rcp_f32_e32 v137, v137
	v_mov_b32_e32 v173, 0
	v_pk_add_f32 v[118:119], v[118:119], 1.0 op_sel_hi:[1,0]
	s_nop 0
	v_rcp_f32_e32 v118, v118
	v_rcp_f32_e32 v119, v119
	v_pk_mul_f32 v[54:55], v[54:55], v[136:137]
	v_pk_mul_f32 v[120:121], v[120:121], v[118:119]
	v_pk_mul_f32 v[118:119], v[44:45], s[0:1] op_sel_hi:[1,0]
	v_pk_mul_f32 v[44:45], v[44:45], v[56:57]
	v_exp_f32_e32 v118, v118
	v_exp_f32_e32 v119, v119
	s_nop 0
	v_pk_add_f32 v[118:119], v[118:119], 1.0 op_sel_hi:[1,0]
	s_nop 0
	v_rcp_f32_e32 v118, v118
	v_rcp_f32_e32 v119, v119
	s_nop 0
	v_pk_mul_f32 v[44:45], v[44:45], v[118:119]
	v_cvt_pk_bf16_f32 v118, v42, v43
	v_cvt_pk_bf16_f32 v119, v54, v55
	v_cvt_pk_bf16_f32 v96, v96, v97
	v_cvt_pk_bf16_f32 v97, v132, v133
	v_cvt_pk_bf16_f32 v54, v104, v105
	v_cvt_pk_bf16_f32 v55, v120, v121
	v_cvt_pk_bf16_f32 v42, v130, v131
	s_nop 0
	v_cvt_pk_bf16_f32 v43, v44, v45
	v_or_b32_e32 v44, 4, v236
	v_ashrrev_i32_e32 v45, 31, v44
	v_lshlrev_b64 v[44:45], 2, v[44:45]
	v_lshl_add_u64 v[174:175], s[18:19], 0, v[44:45]
	v_lshl_add_u64 v[176:177], s[50:51], 0, v[44:45]
	v_lshl_add_u64 v[178:179], s[44:45], 0, v[44:45]
	v_lshl_add_u64 v[180:181], s[20:21], 0, v[44:45]
	v_lshl_add_u64 v[182:183], s[42:43], 0, v[44:45]
	v_lshl_add_u64 v[184:185], s[48:49], 0, v[44:45]
	global_load_dwordx4 v[130:133], v[78:79], off offset:16
	global_load_dwordx4 v[142:145], v[174:175], off
	global_load_dwordx4 v[154:157], v[176:177], off
	global_load_dwordx4 v[158:161], v[222:223], off offset:16
	global_load_dwordx4 v[134:137], v[178:179], off
	global_load_dwordx4 v[150:153], v[180:181], off
	global_load_dwordx4 v[162:165], v[182:183], off
	global_load_dwordx4 v[166:169], v[184:185], off
	v_mov_b32_e32 v104, 0
	v_mov_b32_e32 v105, 0
	s_cbranch_vccnz .LBB0_105
	ds_read_b128 v[170:173], v94 offset:272
	ds_read_b128 v[102:105], v94 offset:304
.LBB0_105:
	v_cvt_f32_i32_e32 v33, v33
	v_cvt_f32_i32_e32 v32, v32
	v_cvt_f32_i32_e32 v31, v31
	v_cvt_f32_i32_e32 v30, v30
	v_cvt_f32_i32_e32 v27, v27
	v_cvt_f32_i32_e32 v26, v26
	v_mov_b32_e32 v44, v238
	v_mov_b32_e32 v45, v238
	v_cvt_f32_i32_e32 v29, v29
	v_cvt_f32_i32_e32 v28, v28
	v_mov_b32_e32 v239, v238
	v_pk_mul_f32 v[56:57], v[20:21], v[44:45]
	v_pk_mul_f32 v[120:121], v[18:19], v[238:239]
	v_pk_mul_f32 v[56:57], v[56:57], v[32:33]
	v_pk_mul_f32 v[32:33], v[22:23], v[238:239]
	v_readlane_b32 s0, v255, 0
	v_pk_mul_f32 v[120:121], v[120:121], v[30:31]
	v_pk_mul_f32 v[30:31], v[24:25], v[44:45]
	v_pk_mul_f32 v[186:187], v[32:33], v[26:27]
	v_add_u32_e32 v26, s0, v94
	v_readlane_b32 s0, v255, 1
	v_pk_mul_f32 v[44:45], v[30:31], v[28:29]
	ds_read_b128 v[26:29], v26
	v_add_u32_e32 v30, s0, v94
	ds_read_b128 v[30:33], v30
	s_waitcnt vmcnt(4)
	v_pk_fma_f32 v[188:189], v[110:111], v[154:155], v[158:159]
	s_waitcnt lgkmcnt(3)
	v_mov_b32_dpp v170, v58 row_shr:1 row_mask:0xf bank_mask:0xf
	v_mov_b32_dpp v171, v59 row_shr:1 row_mask:0xf bank_mask:0xf
	v_pk_fma_f32 v[188:189], v[146:147], v[142:143], v[188:189]
	s_waitcnt lgkmcnt(1)
	v_mov_b32_dpp v26, v146 row_shl:1 row_mask:0xf bank_mask:0xf
	v_mov_b32_dpp v27, v147 row_shl:1 row_mask:0xf bank_mask:0xf
	v_pk_fma_f32 v[170:171], v[130:131], v[170:171], v[188:189]
	v_pk_fma_f32 v[188:189], v[120:121], v[154:155], v[158:159]
	s_waitcnt lgkmcnt(0)
; __device__ __forceinline__ float dpp_shr1(float old, float v) { return __builtin_bit_cast(float, __builtin_amdgcn_update_dpp(__builtin_bit_cast(int, old), __builtin_bit_cast(int, v), 0x111, 0xf, 0xf, false)); }
; #define PAIR(v) (h == 0 ? __builtin_shufflevector(v, v, 0, 1) : __builtin_shufflevector(v, v, 2, 3))
;     __device__ __forceinline__ void operator()(const f32x4 (&acc)[2][2][4][2], const Unit& u, int wr, int wc, int fr_, int fq_) const {
;     ...
;                     const f32x2 g0 = PAIR(z[ai][0][0][n]), g1 = PAIR(z[ai][0][1][n]), g2 = PAIR(z[ai][0][2][n]), g3 = PAIR(z[ai][0][3][n]);
;                     const f32x2 u0 = PAIR(z[ai][1][0][n]), u1 = PAIR(z[ai][1][1][n]), u2 = PAIR(z[ai][1][2][n]), u3 = PAIR(z[ai][1][3][n]);
;                     const f32x2 pBg2 = PAIR(pBg), nBg2 = PAIR(nBg), pBu2 = PAIR(pBu), nBu2 = PAIR(nBu);
;                     f32x2 pg, ng, pu, nu;
;                     pg.x = dpp_shr1(pBg2.x, g3.x); pg.y = dpp_shr1(pBg2.y, g3.y); ng.x = dpp_shl1(nBg2.x, g0.x); ng.y = dpp_shl1(nBg2.y, g0.y);
;                     pu.x = dpp_shr1(pBu2.x, u3.x); pu.y = dpp_shr1(pBu2.y, u3.y); nu.x = dpp_shl1(nBu2.x, u0.x); nu.y = dpp_shl1(nBu2.y, u0.y);
;                     const f32x2 A0 = PAIR(w0g), A1 = PAIR(w1g), A2 = PAIR(w2g), AB = PAIR(bg), C0 = PAIR(w0u), C1 = PAIR(w1u), C2 = PAIR(w2u), CB = PAIR(bu);
;                     f32x2 G[4], U[4];
;                     G[0] = A0 * pg + (A1 * g0 + (A2 * g1 + AB)); G[1] = A0 * g0 + (A1 * g1 + (A2 * g2 + AB)); G[2] = A0 * g1 + (A1 * g2 + (A2 * g3 + AB)); G[3] = A0 * g2 + (A1 * g3 + (A2 * ng + AB));
;                     U[0] = C0 * pu + (C1 * u0 + (C2 * u1 + CB)); U[1] = C0 * u0 + (C1 * u1 + (C2 * u2 + CB)); U[2] = C0 * u1 + (C1 * u2 + (C2 * u3 + CB)); U[3] = C0 * u2 + (C1 * u3 + (C2 * nu + CB));
; #pragma unroll
;                     for (int m = 0; m < 4; ++m) {
;                         const f32x2 t = G[m] * (-1.4426950408889634f);
;                         f32x2 e; e.x = __builtin_amdgcn_exp2f(t.x); e.y = __builtin_amdgcn_exp2f(t.y);
;                         const f32x2 d = e + 1.0f;
;                         f32x2 r; r.x = __builtin_amdgcn_rcpf(d.x); r.y = __builtin_amdgcn_rcpf(d.y);
;                         const f32x2 q = (G[m] * U[m]) * r;
;                         o[m][2 * h] = q.x; o[m][2 * h + 1] = q.y;
;                     }
	v_mov_b32_dpp v30, v138 row_shl:1 row_mask:0xf bank_mask:0xf
	v_mov_b32_dpp v31, v139 row_shl:1 row_mask:0xf bank_mask:0xf
	v_pk_fma_f32 v[188:189], v[110:111], v[142:143], v[188:189]
	v_pk_fma_f32 v[26:27], v[154:155], v[26:27], v[158:159]
	v_pk_fma_f32 v[146:147], v[146:147], v[130:131], v[188:189]
	v_pk_fma_f32 v[188:189], v[58:59], v[154:155], v[158:159]
	v_pk_fma_f32 v[26:27], v[58:59], v[142:143], v[26:27]
	s_waitcnt vmcnt(0)
	s_mov_b64 s[98:99], exec
	s_mov_b32 s100, 0x10001
	s_mov_b32 s101, 0x10001
	s_mov_b64 exec, s[100:101]
	ds_write_b128 v208, v[130:133] offset:512
	ds_write_b128 v208, v[142:145] offset:576
	ds_write_b128 v208, v[154:157] offset:640
	ds_write_b128 v208, v[158:161] offset:704
	ds_write_b128 v208, v[134:137] offset:768
	ds_write_b128 v208, v[150:153] offset:832
	ds_write_b128 v208, v[162:165] offset:896
	ds_write_b128 v208, v[166:169] offset:960
	s_mov_b64 exec, s[98:99]
	v_pk_fma_f32 v[30:31], v[162:163], v[30:31], v[166:167]
	s_mov_b32 s0, 0xbfb8aa3b
	v_mov_b32_dpp v102, v62 row_shr:1 row_mask:0xf bank_mask:0xf
	v_mov_b32_dpp v103, v63 row_shr:1 row_mask:0xf bank_mask:0xf
	v_pk_fma_f32 v[188:189], v[120:121], v[142:143], v[188:189]
	v_pk_fma_f32 v[26:27], v[120:121], v[130:131], v[26:27]
	v_pk_fma_f32 v[120:121], v[62:63], v[162:163], v[166:167]
	v_pk_fma_f32 v[30:31], v[62:63], v[150:151], v[30:31]
	v_pk_mul_f32 v[62:63], v[170:171], s[0:1] op_sel_hi:[1,0]
	v_pk_fma_f32 v[58:59], v[98:99], v[162:163], v[166:167]
	v_exp_f32_e32 v62, v62
	v_exp_f32_e32 v63, v63
	v_pk_fma_f32 v[58:59], v[138:139], v[150:151], v[58:59]
	v_pk_fma_f32 v[110:111], v[110:111], v[130:131], v[188:189]
	v_pk_fma_f32 v[58:59], v[134:135], v[102:103], v[58:59]
	v_pk_add_f32 v[62:63], v[62:63], 1.0 op_sel_hi:[1,0]
	v_pk_fma_f32 v[102:103], v[186:187], v[162:163], v[166:167]
	v_rcp_f32_e32 v62, v62
	v_rcp_f32_e32 v63, v63
	v_pk_fma_f32 v[102:103], v[98:99], v[150:151], v[102:103]
	v_pk_fma_f32 v[120:121], v[186:187], v[150:151], v[120:121]
	v_pk_fma_f32 v[102:103], v[138:139], v[134:135], v[102:103]
	v_pk_mul_f32 v[58:59], v[170:171], v[58:59]
	v_pk_fma_f32 v[98:99], v[98:99], v[134:135], v[120:121]
	v_pk_mul_f32 v[120:121], v[146:147], s[0:1] op_sel_hi:[1,0]
	v_pk_mul_f32 v[58:59], v[58:59], v[62:63]
	v_pk_mul_f32 v[62:63], v[146:147], v[102:103]
	v_pk_mul_f32 v[102:103], v[110:111], s[0:1] op_sel_hi:[1,0]
	v_exp_f32_e32 v120, v120
	v_exp_f32_e32 v121, v121
	v_exp_f32_e32 v102, v102
	v_exp_f32_e32 v103, v103
	v_mov_b32_dpp v28, v148 row_shl:1 row_mask:0xf bank_mask:0xf
	v_pk_add_f32 v[120:121], v[120:121], 1.0 op_sel_hi:[1,0]
	v_mov_b32_dpp v29, v149 row_shl:1 row_mask:0xf bank_mask:0xf
	v_pk_add_f32 v[102:103], v[102:103], 1.0 op_sel_hi:[1,0]
	v_rcp_f32_e32 v120, v120
	v_rcp_f32_e32 v121, v121
	v_rcp_f32_e32 v102, v102
	v_rcp_f32_e32 v103, v103
	v_pk_fma_f32 v[28:29], v[156:157], v[28:29], v[160:161]
	v_pk_fma_f32 v[30:31], v[186:187], v[134:135], v[30:31]
	v_pk_mul_f32 v[98:99], v[110:111], v[98:99]
	v_pk_fma_f32 v[110:111], v[60:61], v[156:157], v[160:161]
	v_pk_fma_f32 v[28:29], v[60:61], v[144:145], v[28:29]
	v_pk_mul_f32 v[62:63], v[62:63], v[120:121]
	v_pk_mul_f32 v[120:121], v[26:27], s[0:1] op_sel_hi:[1,0]
	v_pk_mul_f32 v[102:103], v[98:99], v[102:103]
	v_pk_mul_f32 v[26:27], v[26:27], v[30:31]
	v_mov_b32_dpp v32, v140 row_shl:1 row_mask:0xf bank_mask:0xf
	v_mov_b32_dpp v33, v141 row_shl:1 row_mask:0xf bank_mask:0xf
	v_pk_fma_f32 v[30:31], v[112:113], v[156:157], v[160:161]
	v_pk_fma_f32 v[98:99], v[56:57], v[156:157], v[160:161]
	v_pk_fma_f32 v[110:111], v[56:57], v[144:145], v[110:111]
	v_pk_fma_f32 v[28:29], v[56:57], v[132:133], v[28:29]
	v_pk_fma_f32 v[56:57], v[100:101], v[164:165], v[168:169]
	v_mov_b32_dpp v172, v60 row_shr:1 row_mask:0xf bank_mask:0xf
	v_mov_b32_dpp v173, v61 row_shr:1 row_mask:0xf bank_mask:0xf
	v_mov_b32_dpp v104, v64 row_shr:1 row_mask:0xf bank_mask:0xf
	v_mov_b32_dpp v105, v65 row_shr:1 row_mask:0xf bank_mask:0xf
	v_pk_fma_f32 v[30:31], v[148:149], v[144:145], v[30:31]
	v_pk_fma_f32 v[56:57], v[140:141], v[152:153], v[56:57]
	v_pk_fma_f32 v[32:33], v[164:165], v[32:33], v[168:169]
	v_pk_fma_f32 v[30:31], v[132:133], v[172:173], v[30:31]
	v_pk_fma_f32 v[56:57], v[136:137], v[104:105], v[56:57]
	v_pk_fma_f32 v[104:105], v[64:65], v[164:165], v[168:169]
	v_pk_fma_f32 v[32:33], v[64:65], v[152:153], v[32:33]
	v_pk_fma_f32 v[60:61], v[44:45], v[164:165], v[168:169]
	v_pk_fma_f32 v[104:105], v[44:45], v[152:153], v[104:105]
	v_pk_fma_f32 v[32:33], v[44:45], v[136:137], v[32:33]
	v_pk_mul_f32 v[44:45], v[30:31], s[0:1] op_sel_hi:[1,0]
	v_pk_fma_f32 v[98:99], v[112:113], v[144:145], v[98:99]
	v_exp_f32_e32 v44, v44
	v_exp_f32_e32 v45, v45
	v_pk_fma_f32 v[98:99], v[148:149], v[132:133], v[98:99]
	v_pk_fma_f32 v[60:61], v[100:101], v[152:153], v[60:61]
	v_pk_fma_f32 v[110:111], v[112:113], v[132:133], v[110:111]
	v_pk_add_f32 v[44:45], v[44:45], 1.0 op_sel_hi:[1,0]
	v_pk_fma_f32 v[60:61], v[140:141], v[136:137], v[60:61]
	v_rcp_f32_e32 v44, v44
	v_rcp_f32_e32 v45, v45
	v_pk_mul_f32 v[64:65], v[98:99], s[0:1] op_sel_hi:[1,0]
	v_pk_mul_f32 v[30:31], v[30:31], v[56:57]
	v_exp_f32_e32 v120, v120
	v_exp_f32_e32 v121, v121
	v_exp_f32_e32 v64, v64
	v_exp_f32_e32 v65, v65
	v_pk_mul_f32 v[30:31], v[30:31], v[44:45]
	v_pk_mul_f32 v[44:45], v[98:99], v[60:61]
	v_pk_mul_f32 v[56:57], v[110:111], s[0:1] op_sel_hi:[1,0]
	v_pk_mul_f32 v[60:61], v[28:29], s[0:1] op_sel_hi:[1,0]
	v_exp_f32_e32 v56, v56
	v_exp_f32_e32 v57, v57
	v_exp_f32_e32 v60, v60
	v_exp_f32_e32 v61, v61
	v_pk_add_f32 v[120:121], v[120:121], 1.0 op_sel_hi:[1,0]
	v_pk_add_f32 v[64:65], v[64:65], 1.0 op_sel_hi:[1,0]
	v_rcp_f32_e32 v120, v120
	v_rcp_f32_e32 v121, v121
; __device__ __forceinline__ unsigned cvt_pk_bf16(float lo, float hi) { unsigned r; asm volatile("v_cvt_pk_bf16_f32 %0, %1, %2" : "=v"(r) : "v"(lo), "v"(hi)); return r; }
;     __device__ __forceinline__ void operator()(const f32x4 (&acc)[2][2][4][2], const Unit& u, int wr, int wc, int fr_, int fq_) const {
;     ...
;             for (int n = 0; n < 2; ++n) {
;                 const int ch = ch0 + 4 * n;
;                 const f32x4 w0g = *(const f32x4*)(cw + ch), w1g = *(const f32x4*)(cw + NZ_ + ch), w2g = *(const f32x4*)(cw + 2 * NZ_ + ch), bg = *(const f32x4*)(cb + ch);
;                 const f32x4 w0u = *(const f32x4*)(cw + DFF_ + ch), w1u = *(const f32x4*)(cw + NZ_ + DFF_ + ch), w2u = *(const f32x4*)(cw + 2 * NZ_ + DFF_ + ch), bu = *(const f32x4*)(cb + DFF_ + ch);
;                 f32x4 pBg = zero4, pBu = zero4, nBg = zero4, nBu = zero4;
;                 if (wr == 1) { pBg = X4[XIDX(0, ai, 1) + n]; pBu = X4[XIDX(0, ai, 1) + 2 + n]; }
;                 else if (ai == 1) { pBg = X4[XIDX(1, 0, 1) + n]; pBu = X4[XIDX(1, 0, 1) + 2 + n]; }
;                 if (wr == 0) { nBg = X4[XIDX(1, ai, 0) + n]; nBu = X4[XIDX(1, ai, 0) + 2 + n]; }
;                 else if (ai == 0) { nBg = X4[XIDX(0, 1, 0) + n]; nBu = X4[XIDX(0, 1, 0) + 2 + n]; }
;     ...
;                 for (int m = 0; m < 4; ++m) { ow[m][2 * n] = cvt_pk_bf16(o[m][0], o[m][1]); ow[m][2 * n + 1] = cvt_pk_bf16(o[m][2], o[m][3]); }
;             }
; #pragma unroll
;             for (int m = 0; m < 4; ++m) { u32x4 w; w.x = ow[m][0]; w.y = ow[m][1]; w.z = ow[m][2]; w.w = ow[m][3];
;                 *(u32x4*)(ACT + (size_t)(rowb + ai * HALF + m) * DFF_ + ch0) = w; }
	v_rcp_f32_e32 v64, v64
	v_rcp_f32_e32 v65, v65
	v_pk_add_f32 v[56:57], v[56:57], 1.0 op_sel_hi:[1,0]
	v_pk_add_f32 v[60:61], v[60:61], 1.0 op_sel_hi:[1,0]
	v_rcp_f32_e32 v56, v56
	v_rcp_f32_e32 v57, v57
	v_rcp_f32_e32 v60, v60
	v_rcp_f32_e32 v61, v61
	v_pk_fma_f32 v[100:101], v[100:101], v[136:137], v[104:105]
	v_readlane_b32 s0, v252, 18
	v_pk_mul_f32 v[26:27], v[26:27], v[120:121]
	v_pk_mul_f32 v[44:45], v[44:45], v[64:65]
	v_pk_mul_f32 v[64:65], v[110:111], v[100:101]
	v_pk_mul_f32 v[28:29], v[28:29], v[32:33]
	v_readlane_b32 s1, v252, 19
	v_pk_mul_f32 v[64:65], v[64:65], v[56:57]
	v_pk_mul_f32 v[28:29], v[28:29], v[60:61]
	v_cvt_pk_bf16_f32 v120, v58, v59
	v_cvt_pk_bf16_f32 v121, v30, v31
	v_cvt_pk_bf16_f32 v98, v62, v63
	v_cvt_pk_bf16_f32 v99, v44, v45
	v_cvt_pk_bf16_f32 v56, v102, v103
	v_cvt_pk_bf16_f32 v57, v64, v65
	v_cvt_pk_bf16_f32 v44, v26, v27
	v_mov_b64_e32 v[26:27], s[0:1]
	s_movk_i32 s4, 0x2c00
	v_cvt_pk_bf16_f32 v45, v28, v29
	v_mad_i64_i32 v[28:29], s[0:1], v220, s4, v[26:27]
	v_lshlrev_b64 v[142:143], 1, v[236:237]
	v_or_b32_e32 v190, 1, v220
	v_lshl_add_u64 v[28:29], v[28:29], 0, v[142:143]
	global_store_dwordx4 v[28:29], v[118:121], off
	v_mad_i64_i32 v[28:29], s[0:1], v190, s4, v[26:27]
	v_or_b32_e32 v191, 2, v220
	v_or_b32_e32 v192, 3, v220
	v_lshl_add_u64 v[28:29], v[28:29], 0, v[142:143]
	global_store_dwordx4 v[28:29], v[96:99], off
	v_mad_i64_i32 v[28:29], s[0:1], v191, s4, v[26:27]
	v_mad_i64_i32 v[26:27], s[0:1], v192, s4, v[26:27]
	v_lshl_add_u64 v[28:29], v[28:29], 0, v[142:143]
	v_lshl_add_u64 v[26:27], v[26:27], 0, v[142:143]
	global_store_dwordx4 v[28:29], v[54:57], off
	global_store_dwordx4 v[26:27], v[42:45], off
	ds_read_b128 v[62:65], v208 offset:0
	ds_read_b128 v[96:99], v208 offset:64
	ds_read_b128 v[100:103], v208 offset:128
	ds_read_b128 v[110:113], v208 offset:192
	ds_read_b128 v[28:31], v208 offset:256
	ds_read_b128 v[42:45], v208 offset:320
	ds_read_b128 v[54:57], v208 offset:384
	ds_read_b128 v[58:61], v208 offset:448
	v_readlane_b32 s0, v255, 12
	v_add_u32_e32 v26, 0x1100, v94
	v_add_u32_e32 v104, 0x1120, v94
	v_add_u32_e32 v33, s0, v205
	v_add_u32_e32 v27, 0x100, v33
	v_add_u32_e32 v32, 0x120, v33
	v_cndmask_b32_e64 v26, v26, v27, s[46:47]
	v_cndmask_b32_e64 v32, v104, v32, s[46:47]
	ds_read_b128 v[134:137], v26
	ds_read_b128 v[118:121], v32
	v_readlane_b32 s4, v254, 44
	v_readlane_b32 s5, v254, 45
	v_mov_b32_e32 v26, 0
	s_andn2_b64 vcc, exec, s[4:5]
	v_cndmask_b32_e64 v27, 0, 1, s[4:5]
	v_cmp_ne_u32_e64 s[0:1], 1, v27
	v_mov_b32_e32 v138, 0
	v_mov_b32_e32 v139, 0
	v_mov_b32_e32 v140, 0
	v_mov_b32_e32 v141, 0
	v_mov_b32_e32 v130, 0
	v_mov_b32_e32 v131, 0
	v_mov_b32_e32 v132, 0
	v_mov_b32_e32 v133, 0
	v_mov_b32_e32 v244, v206
	v_mov_b32_e32 v246, v202
	v_mov_b32_e32 v202, v207
	v_mov_b32_e32 v245, v221
	s_cbranch_vccnz .LBB0_107
	ds_read_b128 v[138:141], v33 offset:4096
	ds_read_b128 v[130:133], v33 offset:4128
.LBB0_107:
	v_ffbh_u32_e32 v27, v81
	v_min_u32_e32 v27, 32, v27
	v_lshlrev_b64 v[80:81], v27, v[80:81]
	v_min_u32_e32 v32, 1, v80
	v_or_b32_e32 v32, v81, v32
	v_cvt_f32_u32_e32 v32, v32
	v_sub_u32_e32 v27, 32, v27
	v_cvt_f32_i32_e32 v81, v15
	v_cvt_f32_i32_e32 v80, v14
	v_ldexp_f32 v27, v32, v27
	v_fmamk_f32 v27, v27, 0x2e000000, v204
	v_cmp_gt_f32_e32 vcc, s17, v27
	v_mul_f32_e32 v32, 0x4b800000, v27
	v_cvt_f32_i32_e32 v15, v17
	v_cndmask_b32_e32 v27, v27, v32, vcc
	v_rsq_f32_e32 v27, v27
	v_cvt_f32_i32_e32 v14, v16
	v_cvt_f32_i32_e32 v11, v11
	v_cvt_f32_i32_e32 v10, v10
	v_mul_f32_e32 v32, 0x45800000, v27
	v_cndmask_b32_e32 v27, v27, v32, vcc
	v_mul_f32_e32 v32, v95, v27
	v_cvt_f32_i32_e32 v13, v13
	v_cvt_f32_i32_e32 v12, v12
	v_pk_mul_f32 v[16:17], v[38:39], v[32:33] op_sel_hi:[1,0]
	v_pk_mul_f32 v[38:39], v[40:41], v[32:33] op_sel_hi:[1,0]
	v_pk_mul_f32 v[34:35], v[34:35], v[32:33] op_sel_hi:[1,0]
	v_pk_mul_f32 v[14:15], v[38:39], v[14:15]
	v_pk_mul_f32 v[38:39], v[16:17], v[80:81]
	v_pk_mul_f32 v[16:17], v[36:37], v[32:33] op_sel_hi:[1,0]
	s_waitcnt lgkmcnt(0)
	v_pk_fma_f32 v[36:37], v[126:127], v[100:101], v[110:111]
	v_pk_mul_f32 v[10:11], v[34:35], v[10:11]
	s_waitcnt lgkmcnt(1)
	v_mov_b32_dpp v138, v106 row_shl:1 row_mask:0xf bank_mask:0xf
	v_mov_b32_dpp v139, v107 row_shl:1 row_mask:0xf bank_mask:0xf
	v_pk_fma_f32 v[34:35], v[90:91], v[100:101], v[110:111]
	v_pk_fma_f32 v[36:37], v[90:91], v[96:97], v[36:37]
	v_pk_mul_f32 v[16:17], v[16:17], v[12:13]
	v_pk_fma_f32 v[12:13], v[38:39], v[100:101], v[110:111]
	v_pk_fma_f32 v[34:35], v[38:39], v[96:97], v[34:35]
	v_pk_fma_f32 v[36:37], v[38:39], v[62:63], v[36:37]
	v_pk_fma_f32 v[38:39], v[100:101], v[138:139], v[110:111]
	v_mov_b32_dpp v134, v126 row_shr:1 row_mask:0xf bank_mask:0xf
	v_mov_b32_dpp v135, v127 row_shr:1 row_mask:0xf bank_mask:0xf
	v_pk_fma_f32 v[12:13], v[106:107], v[96:97], v[12:13]
	v_pk_fma_f32 v[38:39], v[126:127], v[96:97], v[38:39]
	v_pk_fma_f32 v[80:81], v[122:123], v[54:55], v[58:59]
	s_waitcnt lgkmcnt(0)
;     __device__ __forceinline__ void operator()(const f32x4 (&acc)[2][2][4][2], const Unit& u, int wr, int wc, int fr_, int fq_) const {
;     ...
;                 const f32x4 w0g = *(const f32x4*)(cw + ch), w1g = *(const f32x4*)(cw + NZ_ + ch), w2g = *(const f32x4*)(cw + 2 * NZ_ + ch), bg = *(const f32x4*)(cb + ch);
;     ...
;                     const f32x2 g0 = PAIR(z[ai][0][0][n]), g1 = PAIR(z[ai][0][1][n]), g2 = PAIR(z[ai][0][2][n]), g3 = PAIR(z[ai][0][3][n]);
;                     const f32x2 u0 = PAIR(z[ai][1][0][n]), u1 = PAIR(z[ai][1][1][n]), u2 = PAIR(z[ai][1][2][n]), u3 = PAIR(z[ai][1][3][n]);
;                     const f32x2 pBg2 = PAIR(pBg), nBg2 = PAIR(nBg), pBu2 = PAIR(pBu), nBu2 = PAIR(nBu);
;                     f32x2 pg, ng, pu, nu;
;                     pg.x = dpp_shr1(pBg2.x, g3.x); pg.y = dpp_shr1(pBg2.y, g3.y); ng.x = dpp_shl1(nBg2.x, g0.x); ng.y = dpp_shl1(nBg2.y, g0.y);
;                     pu.x = dpp_shr1(pBu2.x, u3.x); pu.y = dpp_shr1(pBu2.y, u3.y); nu.x = dpp_shl1(nBu2.x, u0.x); nu.y = dpp_shl1(nBu2.y, u0.y);
;                     const f32x2 A0 = PAIR(w0g), A1 = PAIR(w1g), A2 = PAIR(w2g), AB = PAIR(bg), C0 = PAIR(w0u), C1 = PAIR(w1u), C2 = PAIR(w2u), CB = PAIR(bu);
;                     f32x2 G[4], U[4];
;                     G[0] = A0 * pg + (A1 * g0 + (A2 * g1 + AB)); G[1] = A0 * g0 + (A1 * g1 + (A2 * g2 + AB)); G[2] = A0 * g1 + (A1 * g2 + (A2 * g3 + AB)); G[3] = A0 * g2 + (A1 * g3 + (A2 * ng + AB));
;                     U[0] = C0 * pu + (C1 * u0 + (C2 * u1 + CB)); U[1] = C0 * u0 + (C1 * u1 + (C2 * u2 + CB)); U[2] = C0 * u1 + (C1 * u2 + (C2 * u3 + CB)); U[3] = C0 * u2 + (C1 * u3 + (C2 * nu + CB));
; #pragma unroll
;                     for (int m = 0; m < 4; ++m) {
;                         const f32x2 t = G[m] * (-1.4426950408889634f);
;                         f32x2 e; e.x = __builtin_amdgcn_exp2f(t.x); e.y = __builtin_amdgcn_exp2f(t.y);
;                         const f32x2 d = e + 1.0f;
;                         f32x2 r; r.x = __builtin_amdgcn_rcpf(d.x); r.y = __builtin_amdgcn_rcpf(d.y);
;                         const f32x2 q = (G[m] * U[m]) * r;
;                         o[m][2 * h] = q.x; o[m][2 * h + 1] = q.y;
;                     }
;     ...
;                 }
; #pragma unroll
;                 for (int m = 0; m < 4; ++m) { ow[m][2 * n] = cvt_pk_bf16(o[m][0], o[m][1]); ow[m][2 * n + 1] = cvt_pk_bf16(o[m][2], o[m][3]); }
	v_mov_b32_dpp v130, v114 row_shl:1 row_mask:0xf bank_mask:0xf
	v_mov_b32_dpp v131, v115 row_shl:1 row_mask:0xf bank_mask:0xf
	v_pk_fma_f32 v[12:13], v[62:63], v[134:135], v[12:13]
	v_pk_fma_f32 v[34:35], v[106:107], v[62:63], v[34:35]
	v_pk_fma_f32 v[38:39], v[90:91], v[62:63], v[38:39]
	v_pk_fma_f32 v[62:63], v[82:83], v[54:55], v[58:59]
	v_pk_fma_f32 v[80:81], v[82:83], v[42:43], v[80:81]
	v_pk_fma_f32 v[40:41], v[10:11], v[54:55], v[58:59]
	v_pk_fma_f32 v[62:63], v[10:11], v[42:43], v[62:63]
	v_pk_fma_f32 v[80:81], v[10:11], v[28:29], v[80:81]
	v_pk_fma_f32 v[10:11], v[54:55], v[130:131], v[58:59]
	s_mov_b32 s4, 0xbfb8aa3b
	v_pk_fma_f32 v[10:11], v[122:123], v[42:43], v[10:11]
	v_pk_fma_f32 v[40:41], v[114:115], v[42:43], v[40:41]
	v_pk_fma_f32 v[42:43], v[82:83], v[28:29], v[10:11]
	v_pk_mul_f32 v[10:11], v[12:13], s[4:5] op_sel_hi:[1,0]
	v_mov_b32_dpp v118, v122 row_shr:1 row_mask:0xf bank_mask:0xf
	v_exp_f32_e32 v10, v10
	v_exp_f32_e32 v11, v11
	v_mov_b32_dpp v119, v123 row_shr:1 row_mask:0xf bank_mask:0xf
	v_pk_fma_f32 v[40:41], v[28:29], v[118:119], v[40:41]
	v_pk_fma_f32 v[62:63], v[114:115], v[28:29], v[62:63]
	v_pk_add_f32 v[10:11], v[10:11], 1.0 op_sel_hi:[1,0]
	v_pk_mul_f32 v[12:13], v[12:13], v[40:41]
	v_rcp_f32_e32 v10, v10
	v_rcp_f32_e32 v11, v11
	v_pk_mul_f32 v[28:29], v[34:35], v[62:63]
	v_mov_b32_dpp v132, v116 row_shl:1 row_mask:0xf bank_mask:0xf
	v_mov_b32_dpp v133, v117 row_shl:1 row_mask:0xf bank_mask:0xf
	v_pk_mul_f32 v[10:11], v[12:13], v[10:11]
	v_pk_mul_f32 v[12:13], v[34:35], s[4:5] op_sel_hi:[1,0]
	v_pk_mul_f32 v[34:35], v[36:37], v[80:81]
	v_exp_f32_e32 v12, v12
	v_exp_f32_e32 v13, v13
	v_mov_b32_dpp v136, v128 row_shr:1 row_mask:0xf bank_mask:0xf
	v_mov_b32_dpp v137, v129 row_shr:1 row_mask:0xf bank_mask:0xf
	v_pk_fma_f32 v[54:55], v[84:85], v[56:57], v[60:61]
	v_pk_add_f32 v[12:13], v[12:13], 1.0 op_sel_hi:[1,0]
	v_pk_fma_f32 v[58:59], v[124:125], v[56:57], v[60:61]
	v_rcp_f32_e32 v12, v12
	v_rcp_f32_e32 v13, v13
	v_mov_b32_dpp v120, v124 row_shr:1 row_mask:0xf bank_mask:0xf
	v_mov_b32_dpp v121, v125 row_shr:1 row_mask:0xf bank_mask:0xf
	v_pk_fma_f32 v[54:55], v[16:17], v[44:45], v[54:55]
	v_pk_mul_f32 v[12:13], v[28:29], v[12:13]
	v_pk_mul_f32 v[28:29], v[36:37], s[4:5] op_sel_hi:[1,0]
	v_pk_mul_f32 v[36:37], v[38:39], v[42:43]
	v_exp_f32_e32 v28, v28
	v_exp_f32_e32 v29, v29
	v_pk_fma_f32 v[42:43], v[16:17], v[56:57], v[60:61]
	v_pk_fma_f32 v[56:57], v[56:57], v[132:133], v[60:61]
	v_pk_fma_f32 v[42:43], v[116:117], v[44:45], v[42:43]
	v_pk_add_f32 v[28:29], v[28:29], 1.0 op_sel_hi:[1,0]
	v_pk_fma_f32 v[58:59], v[84:85], v[44:45], v[58:59]
	v_rcp_f32_e32 v28, v28
	v_rcp_f32_e32 v29, v29
	v_pk_fma_f32 v[44:45], v[124:125], v[44:45], v[56:57]
	v_pk_fma_f32 v[42:43], v[30:31], v[120:121], v[42:43]
	v_pk_fma_f32 v[54:55], v[116:117], v[30:31], v[54:55]
	v_pk_mul_f32 v[28:29], v[34:35], v[28:29]
	v_pk_mul_f32 v[34:35], v[38:39], s[4:5] op_sel_hi:[1,0]
	v_pk_fma_f32 v[16:17], v[16:17], v[30:31], v[58:59]
	v_exp_f32_e32 v34, v34
	v_exp_f32_e32 v35, v35
	v_pk_fma_f32 v[30:31], v[84:85], v[30:31], v[44:45]
	v_pk_fma_f32 v[38:39], v[92:93], v[102:103], v[112:113]
	v_pk_fma_f32 v[40:41], v[128:129], v[102:103], v[112:113]
	v_pk_add_f32 v[34:35], v[34:35], 1.0 op_sel_hi:[1,0]
	v_pk_fma_f32 v[38:39], v[14:15], v[98:99], v[38:39]
	v_rcp_f32_e32 v34, v34
	v_rcp_f32_e32 v35, v35
	v_pk_fma_f32 v[38:39], v[108:109], v[64:65], v[38:39]
	v_pk_fma_f32 v[40:41], v[92:93], v[98:99], v[40:41]
	v_mov_b32_dpp v140, v108 row_shl:1 row_mask:0xf bank_mask:0xf
	v_pk_mul_f32 v[36:37], v[36:37], v[34:35]
	v_pk_fma_f32 v[34:35], v[14:15], v[102:103], v[112:113]
	v_pk_fma_f32 v[14:15], v[14:15], v[64:65], v[40:41]
	v_pk_fma_f32 v[34:35], v[108:109], v[98:99], v[34:35]
	v_mov_b32_dpp v141, v109 row_shl:1 row_mask:0xf bank_mask:0xf
	v_pk_fma_f32 v[34:35], v[64:65], v[136:137], v[34:35]
	v_pk_fma_f32 v[40:41], v[102:103], v[140:141], v[112:113]
	v_pk_mul_f32 v[44:45], v[34:35], s[4:5] op_sel_hi:[1,0]
	v_pk_mul_f32 v[34:35], v[34:35], v[42:43]
	v_exp_f32_e32 v44, v44
	v_exp_f32_e32 v45, v45
	v_pk_fma_f32 v[40:41], v[128:129], v[98:99], v[40:41]
	s_and_b64 vcc, exec, s[0:1]
	v_pk_fma_f32 v[40:41], v[92:93], v[64:65], v[40:41]
	v_pk_add_f32 v[44:45], v[44:45], 1.0 op_sel_hi:[1,0]
	v_pk_mul_f32 v[30:31], v[40:41], v[30:31]
	v_rcp_f32_e32 v44, v44
	v_rcp_f32_e32 v45, v45
	v_mov_b32_e32 v27, 0
	v_mov_b32_e32 v98, 0
	v_mov_b32_e32 v99, 0
	v_pk_mul_f32 v[42:43], v[34:35], v[44:45]
	v_pk_mul_f32 v[34:35], v[38:39], s[4:5] op_sel_hi:[1,0]
	v_pk_mul_f32 v[38:39], v[38:39], v[54:55]
	v_exp_f32_e32 v34, v34
	v_exp_f32_e32 v35, v35
	v_mov_b32_e32 v100, 0
	v_mov_b32_e32 v101, 0
	v_pk_add_f32 v[34:35], v[34:35], 1.0 op_sel_hi:[1,0]
	s_nop 0
	v_rcp_f32_e32 v34, v34
	v_rcp_f32_e32 v35, v35
	s_nop 0
	v_pk_mul_f32 v[38:39], v[38:39], v[34:35]
	v_pk_mul_f32 v[34:35], v[14:15], s[4:5] op_sel_hi:[1,0]
	v_pk_mul_f32 v[14:15], v[14:15], v[16:17]
	v_exp_f32_e32 v34, v34
	v_exp_f32_e32 v35, v35
	s_nop 0
	v_pk_add_f32 v[34:35], v[34:35], 1.0 op_sel_hi:[1,0]
	s_nop 0
	v_rcp_f32_e32 v34, v34
	v_rcp_f32_e32 v35, v35
	s_nop 0
	v_pk_mul_f32 v[16:17], v[14:15], v[34:35]
	v_pk_mul_f32 v[14:15], v[40:41], s[4:5] op_sel_hi:[1,0]
	v_cvt_pk_bf16_f32 v34, v10, v11
	v_cvt_pk_bf16_f32 v35, v42, v43
	s_mov_b32 s5, s29
	v_exp_f32_e32 v14, v14
	v_exp_f32_e32 v15, v15
	s_nop 0
	v_pk_add_f32 v[14:15], v[14:15], 1.0 op_sel_hi:[1,0]
	s_nop 0
	v_rcp_f32_e32 v14, v14
	v_rcp_f32_e32 v15, v15
	s_nop 0
	v_pk_mul_f32 v[40:41], v[30:31], v[14:15]
	v_cvt_pk_bf16_f32 v30, v12, v13
	v_cvt_pk_bf16_f32 v31, v38, v39
	v_cvt_pk_bf16_f32 v14, v28, v29
	v_cvt_pk_bf16_f32 v15, v16, v17
	v_cvt_pk_bf16_f32 v10, v36, v37
	s_nop 0
	v_cvt_pk_bf16_f32 v11, v40, v41
	ds_read_b128 v[62:65], v208 offset:512
	s_nop 0
	ds_read_b128 v[78:81], v208 offset:576
	ds_read_b128 v[82:85], v208 offset:640
	ds_read_b128 v[90:93], v208 offset:704
	ds_read_b128 v[36:39], v208 offset:768
	ds_read_b128 v[40:43], v208 offset:832
	ds_read_b128 v[54:57], v208 offset:896
	ds_read_b128 v[58:61], v208 offset:960
	v_add_u32_e32 v12, 0x110, v33
	v_add_u32_e32 v16, 0x1110, v94
	v_add_u32_e32 v13, 0x130, v33
	v_add_u32_e32 v17, 0x1130, v94
	v_cndmask_b32_e64 v12, v16, v12, s[46:47]
	v_cndmask_b32_e64 v13, v17, v13, s[46:47]
	ds_read_b128 v[102:105], v12
	ds_read_b128 v[94:97], v13
	v_mov_b32_e32 v28, 0
	v_mov_b32_e32 v29, 0
	s_cbranch_vccnz .LBB0_109
	ds_read_b128 v[26:29], v33 offset:4112
	ds_read_b128 v[98:101], v33 offset:4144
; __device__ __forceinline__ float dpp_shr1(float old, float v) { return __builtin_bit_cast(float, __builtin_amdgcn_update_dpp(__builtin_bit_cast(int, old), __builtin_bit_cast(int, v), 0x111, 0xf, 0xf, false)); }
; #define PAIR(v) (h == 0 ? __builtin_shufflevector(v, v, 0, 1) : __builtin_shufflevector(v, v, 2, 3))
;     __device__ __forceinline__ void operator()(const f32x4 (&acc)[2][2][4][2], const Unit& u, int wr, int wc, int fr_, int fq_) const {
;     ...
;                     const f32x2 g0 = PAIR(z[ai][0][0][n]), g1 = PAIR(z[ai][0][1][n]), g2 = PAIR(z[ai][0][2][n]), g3 = PAIR(z[ai][0][3][n]);
;                     const f32x2 u0 = PAIR(z[ai][1][0][n]), u1 = PAIR(z[ai][1][1][n]), u2 = PAIR(z[ai][1][2][n]), u3 = PAIR(z[ai][1][3][n]);
;                     const f32x2 pBg2 = PAIR(pBg), nBg2 = PAIR(nBg), pBu2 = PAIR(pBu), nBu2 = PAIR(nBu);
;                     f32x2 pg, ng, pu, nu;
;                     pg.x = dpp_shr1(pBg2.x, g3.x); pg.y = dpp_shr1(pBg2.y, g3.y); ng.x = dpp_shl1(nBg2.x, g0.x); ng.y = dpp_shl1(nBg2.y, g0.y);
;                     pu.x = dpp_shr1(pBu2.x, u3.x); pu.y = dpp_shr1(pBu2.y, u3.y); nu.x = dpp_shl1(nBu2.x, u0.x); nu.y = dpp_shl1(nBu2.y, u0.y);
;                     const f32x2 A0 = PAIR(w0g), A1 = PAIR(w1g), A2 = PAIR(w2g), AB = PAIR(bg), C0 = PAIR(w0u), C1 = PAIR(w1u), C2 = PAIR(w2u), CB = PAIR(bu);
;                     f32x2 G[4], U[4];
;                     G[0] = A0 * pg + (A1 * g0 + (A2 * g1 + AB)); G[1] = A0 * g0 + (A1 * g1 + (A2 * g2 + AB)); G[2] = A0 * g1 + (A1 * g2 + (A2 * g3 + AB)); G[3] = A0 * g2 + (A1 * g3 + (A2 * ng + AB));
;                     U[0] = C0 * pu + (C1 * u0 + (C2 * u1 + CB)); U[1] = C0 * u0 + (C1 * u1 + (C2 * u2 + CB)); U[2] = C0 * u1 + (C1 * u2 + (C2 * u3 + CB)); U[3] = C0 * u2 + (C1 * u3 + (C2 * nu + CB));
; #pragma unroll
;                     for (int m = 0; m < 4; ++m) {
;                         const f32x2 t = G[m] * (-1.4426950408889634f);
;                         f32x2 e; e.x = __builtin_amdgcn_exp2f(t.x); e.y = __builtin_amdgcn_exp2f(t.y);
;                         const f32x2 d = e + 1.0f;
;                         f32x2 r; r.x = __builtin_amdgcn_rcpf(d.x); r.y = __builtin_amdgcn_rcpf(d.y);
;                         const f32x2 q = (G[m] * U[m]) * r;
;                         o[m][2 * h] = q.x; o[m][2 * h + 1] = q.y;
;                     }
.LBB0_109:
	v_cvt_f32_i32_e32 v9, v9
	v_cvt_f32_i32_e32 v8, v8
	v_mov_b32_e32 v12, v32
	v_mov_b32_e32 v13, v32
	v_cvt_f32_i32_e32 v5, v5
	v_cvt_f32_i32_e32 v4, v4
	s_waitcnt lgkmcnt(1)
	v_mov_b32_dpp v26, v46 row_shl:1 row_mask:0xf bank_mask:0xf
	v_mov_b32_dpp v27, v47 row_shl:1 row_mask:0xf bank_mask:0xf
	v_pk_mul_f32 v[16:17], v[24:25], v[12:13]
	v_cvt_f32_i32_e32 v7, v7
	v_cvt_f32_i32_e32 v6, v6
	v_pk_mul_f32 v[12:13], v[20:21], v[12:13]
	v_mov_b32_e32 v33, v32
	v_pk_mul_f32 v[8:9], v[12:13], v[8:9]
	s_waitcnt lgkmcnt(0)
	v_pk_fma_f32 v[12:13], v[82:83], v[26:27], v[90:91]
	v_pk_mul_f32 v[4:5], v[16:17], v[4:5]
	v_pk_fma_f32 v[12:13], v[66:67], v[78:79], v[12:13]
	v_pk_mul_f32 v[16:17], v[18:19], v[32:33]
	v_pk_fma_f32 v[12:13], v[86:87], v[62:63], v[12:13]
	s_mov_b32 s0, 0xbfb8aa3b
	v_cvt_f32_i32_e32 v3, v3
	v_cvt_f32_i32_e32 v2, v2
	v_pk_mul_f32 v[6:7], v[16:17], v[6:7]
	v_pk_mul_f32 v[16:17], v[12:13], s[0:1] op_sel_hi:[1,0]
	v_pk_fma_f32 v[20:21], v[66:67], v[82:83], v[90:91]
	v_exp_f32_e32 v16, v16
	v_exp_f32_e32 v17, v17
	v_pk_fma_f32 v[20:21], v[86:87], v[78:79], v[20:21]
	v_pk_mul_f32 v[22:23], v[22:23], v[32:33]
	v_pk_fma_f32 v[20:21], v[6:7], v[62:63], v[20:21]
	v_pk_mul_f32 v[2:3], v[22:23], v[2:3]
	v_pk_mul_f32 v[22:23], v[20:21], s[0:1] op_sel_hi:[1,0]
	s_waitcnt lgkmcnt(0)
	v_mov_b32_dpp v98, v50 row_shl:1 row_mask:0xf bank_mask:0xf
	v_mov_b32_dpp v99, v51 row_shl:1 row_mask:0xf bank_mask:0xf
	v_pk_add_f32 v[16:17], v[16:17], 1.0 op_sel_hi:[1,0]
	v_exp_f32_e32 v22, v22
	v_exp_f32_e32 v23, v23
	v_pk_fma_f32 v[18:19], v[54:55], v[98:99], v[58:59]
	v_rcp_f32_e32 v16, v16
	v_rcp_f32_e32 v17, v17
	v_pk_fma_f32 v[18:19], v[70:71], v[40:41], v[18:19]
	v_mov_b32_dpp v102, v66 row_shr:1 row_mask:0xf bank_mask:0xf
	v_pk_fma_f32 v[18:19], v[74:75], v[36:37], v[18:19]
	v_mov_b32_dpp v103, v67 row_shr:1 row_mask:0xf bank_mask:0xf
	v_pk_mul_f32 v[12:13], v[12:13], v[18:19]
	v_pk_add_f32 v[18:19], v[22:23], 1.0 op_sel_hi:[1,0]
	v_pk_mul_f32 v[12:13], v[12:13], v[16:17]
	v_pk_fma_f32 v[16:17], v[70:71], v[54:55], v[58:59]
	v_rcp_f32_e32 v18, v18
	v_rcp_f32_e32 v19, v19
	v_pk_fma_f32 v[16:17], v[74:75], v[40:41], v[16:17]
	v_pk_fma_f32 v[22:23], v[74:75], v[54:55], v[58:59]
	v_pk_fma_f32 v[16:17], v[2:3], v[36:37], v[16:17]
	v_pk_fma_f32 v[22:23], v[2:3], v[40:41], v[22:23]
	v_pk_mul_f32 v[16:17], v[20:21], v[16:17]
	v_pk_fma_f32 v[22:23], v[50:51], v[36:37], v[22:23]
	v_pk_mul_f32 v[16:17], v[16:17], v[18:19]
	v_pk_fma_f32 v[18:19], v[86:87], v[82:83], v[90:91]
	v_pk_fma_f32 v[2:3], v[2:3], v[54:55], v[58:59]
	v_pk_fma_f32 v[18:19], v[6:7], v[78:79], v[18:19]
	v_pk_fma_f32 v[6:7], v[6:7], v[82:83], v[90:91]
	v_pk_fma_f32 v[18:19], v[46:47], v[62:63], v[18:19]
	v_pk_fma_f32 v[6:7], v[46:47], v[78:79], v[6:7]
	v_pk_mul_f32 v[20:21], v[18:19], s[0:1] op_sel_hi:[1,0]
	v_pk_fma_f32 v[6:7], v[62:63], v[102:103], v[6:7]
	v_exp_f32_e32 v20, v20
	v_exp_f32_e32 v21, v21
	v_pk_mul_f32 v[24:25], v[6:7], s[0:1] op_sel_hi:[1,0]
	v_pk_mul_f32 v[18:19], v[18:19], v[22:23]
	v_exp_f32_e32 v24, v24
	v_pk_add_f32 v[20:21], v[20:21], 1.0 op_sel_hi:[1,0]
	v_exp_f32_e32 v25, v25
	v_rcp_f32_e32 v20, v20
	v_rcp_f32_e32 v21, v21
	v_mov_b32_dpp v94, v70 row_shr:1 row_mask:0xf bank_mask:0xf
	v_mov_b32_dpp v95, v71 row_shr:1 row_mask:0xf bank_mask:0xf
	v_pk_fma_f32 v[2:3], v[50:51], v[40:41], v[2:3]
	v_pk_mul_f32 v[18:19], v[18:19], v[20:21]
	v_pk_add_f32 v[20:21], v[24:25], 1.0 op_sel_hi:[1,0]
	v_pk_fma_f32 v[2:3], v[36:37], v[94:95], v[2:3]
	v_rcp_f32_e32 v20, v20
	v_rcp_f32_e32 v21, v21
	v_pk_mul_f32 v[2:3], v[6:7], v[2:3]
	v_pk_fma_f32 v[6:7], v[8:9], v[84:85], v[92:93]
	v_pk_fma_f32 v[22:23], v[68:69], v[84:85], v[92:93]
	v_pk_mul_f32 v[2:3], v[2:3], v[20:21]
	v_pk_fma_f32 v[20:21], v[88:89], v[84:85], v[92:93]
	v_pk_fma_f32 v[24:25], v[4:5], v[56:57], v[60:61]
	v_mov_b32_dpp v104, v68 row_shr:1 row_mask:0xf bank_mask:0xf
	v_mov_b32_dpp v105, v69 row_shr:1 row_mask:0xf bank_mask:0xf
	v_mov_b32_dpp v96, v72 row_shr:1 row_mask:0xf bank_mask:0xf
	v_mov_b32_dpp v97, v73 row_shr:1 row_mask:0xf bank_mask:0xf
	v_pk_fma_f32 v[6:7], v[48:49], v[80:81], v[6:7]
	v_pk_fma_f32 v[20:21], v[8:9], v[80:81], v[20:21]
	v_pk_fma_f32 v[22:23], v[88:89], v[80:81], v[22:23]
	v_pk_fma_f32 v[24:25], v[52:53], v[42:43], v[24:25]
	v_mov_b32_dpp v28, v48 row_shl:1 row_mask:0xf bank_mask:0xf
	v_mov_b32_dpp v29, v49 row_shl:1 row_mask:0xf bank_mask:0xf
	v_pk_fma_f32 v[6:7], v[64:65], v[104:105], v[6:7]
	v_pk_fma_f32 v[20:21], v[48:49], v[64:65], v[20:21]
	v_pk_fma_f32 v[8:9], v[8:9], v[64:65], v[22:23]
	v_pk_fma_f32 v[24:25], v[38:39], v[96:97], v[24:25]
; __device__ __forceinline__ unsigned cvt_pk_bf16(float lo, float hi) { unsigned r; asm volatile("v_cvt_pk_bf16_f32 %0, %1, %2" : "=v"(r) : "v"(lo), "v"(hi)); return r; }
;     __device__ __forceinline__ void operator()(const f32x4 (&acc)[2][2][4][2], const Unit& u, int wr, int wc, int fr_, int fq_) const {
;     ...
;         {   const int hcol = u.pn * BM + wc * 32 + 8 * fq;
;             if (wr == 0 && fr == 0) {
; #pragma unroll
;                 for (int m = 0; m < 2; ++m)
; #pragma unroll
;                     for (int bj = 0; bj < 2; ++bj)
; #pragma unroll
;                         for (int n = 0; n < 2; ++n) *(f32x4*)(HZ + (size_t)(u.pm * 4 + m) * NZ_ + hcol + bj * HALF + 4 * n) = z[0][bj][m][n]; }
;             if (wr == 1 && fr == 15) {
; #pragma unroll
;                 for (int m = 2; m < 4; ++m)
; #pragma unroll
;                     for (int bj = 0; bj < 2; ++bj)
; #pragma unroll
;                         for (int n = 0; n < 2; ++n) *(f32x4*)(HZ + (size_t)(u.pm * 4 + m) * NZ_ + hcol + bj * HALF + 4 * n) = z[1][bj][m][n]; }
;     ...
;                 for (int m = 0; m < 4; ++m) { ow[m][2 * n] = cvt_pk_bf16(o[m][0], o[m][1]); ow[m][2 * n + 1] = cvt_pk_bf16(o[m][2], o[m][3]); }
;             }
; #pragma unroll
;             for (int m = 0; m < 4; ++m) { u32x4 w; w.x = ow[m][0]; w.y = ow[m][1]; w.z = ow[m][2]; w.w = ow[m][3];
;                 *(u32x4*)(ACT + (size_t)(rowb + ai * HALF + m) * DFF_ + ch0) = w; }
	v_pk_fma_f32 v[22:23], v[84:85], v[28:29], v[92:93]
	v_pk_fma_f32 v[26:27], v[76:77], v[56:57], v[60:61]
	v_pk_mul_f32 v[32:33], v[6:7], s[0:1] op_sel_hi:[1,0]
	v_pk_mul_f32 v[36:37], v[20:21], s[0:1] op_sel_hi:[1,0]
	v_pk_mul_f32 v[6:7], v[6:7], v[24:25]
	v_pk_mul_f32 v[24:25], v[8:9], s[0:1] op_sel_hi:[1,0]
	v_pk_fma_f32 v[22:23], v[68:69], v[80:81], v[22:23]
	v_pk_fma_f32 v[26:27], v[4:5], v[42:43], v[26:27]
	v_exp_f32_e32 v36, v36
	v_exp_f32_e32 v37, v37
	v_exp_f32_e32 v24, v24
	v_exp_f32_e32 v25, v25
	v_pk_fma_f32 v[22:23], v[88:89], v[64:65], v[22:23]
	v_pk_fma_f32 v[26:27], v[52:53], v[38:39], v[26:27]
	v_exp_f32_e32 v32, v32
	v_exp_f32_e32 v33, v33
	v_pk_mul_f32 v[20:21], v[20:21], v[26:27]
	v_pk_mul_f32 v[26:27], v[22:23], s[0:1] op_sel_hi:[1,0]
	v_pk_add_f32 v[36:37], v[36:37], 1.0 op_sel_hi:[1,0]
	v_exp_f32_e32 v26, v26
	v_exp_f32_e32 v27, v27
	v_pk_add_f32 v[24:25], v[24:25], 1.0 op_sel_hi:[1,0]
	v_pk_fma_f32 v[28:29], v[72:73], v[56:57], v[60:61]
	v_pk_add_f32 v[32:33], v[32:33], 1.0 op_sel_hi:[1,0]
	v_rcp_f32_e32 v36, v36
	v_rcp_f32_e32 v37, v37
	v_rcp_f32_e32 v24, v24
	v_rcp_f32_e32 v25, v25
	v_pk_fma_f32 v[28:29], v[76:77], v[42:43], v[28:29]
	v_rcp_f32_e32 v32, v32
	v_rcp_f32_e32 v33, v33
	v_mov_b32_dpp v100, v52 row_shl:1 row_mask:0xf bank_mask:0xf
	v_mov_b32_dpp v101, v53 row_shl:1 row_mask:0xf bank_mask:0xf
	v_pk_fma_f32 v[4:5], v[4:5], v[38:39], v[28:29]
	v_pk_add_f32 v[26:27], v[26:27], 1.0 op_sel_hi:[1,0]
	v_readlane_b32 s0, v252, 18
	v_pk_fma_f32 v[28:29], v[56:57], v[100:101], v[60:61]
	v_rcp_f32_e32 v26, v26
	v_rcp_f32_e32 v27, v27
	v_pk_mul_f32 v[4:5], v[8:9], v[4:5]
	v_readlane_b32 s1, v252, 19
	v_add_u32_e32 v44, 0x80, v220
	v_pk_fma_f32 v[28:29], v[72:73], v[42:43], v[28:29]
	v_pk_mul_f32 v[20:21], v[20:21], v[36:37]
	v_pk_mul_f32 v[4:5], v[4:5], v[24:25]
	v_cvt_pk_bf16_f32 v36, v2, v3
	v_mov_b64_e32 v[2:3], s[0:1]
	s_movk_i32 s4, 0x2c00
	v_pk_fma_f32 v[28:29], v[76:77], v[38:39], v[28:29]
	v_pk_mul_f32 v[6:7], v[6:7], v[32:33]
	v_add_u32_e32 v45, 0x81, v220
	v_cvt_pk_bf16_f32 v37, v6, v7
	v_cvt_pk_bf16_f32 v32, v18, v19
	v_cvt_pk_bf16_f32 v33, v20, v21
	v_cvt_pk_bf16_f32 v16, v16, v17
	v_cvt_pk_bf16_f32 v17, v4, v5
	v_mad_i64_i32 v[4:5], s[0:1], v44, s4, v[2:3]
	v_pk_mul_f32 v[8:9], v[22:23], v[28:29]
	v_lshl_add_u64 v[4:5], v[4:5], 0, v[142:143]
	v_pk_mul_f32 v[8:9], v[8:9], v[26:27]
	v_cvt_pk_bf16_f32 v12, v12, v13
	v_add_u32_e32 v106, 0x82, v220
	v_cvt_pk_bf16_f32 v13, v8, v9
	global_store_dwordx4 v[4:5], v[34:37], off
	v_mad_i64_i32 v[4:5], s[0:1], v45, s4, v[2:3]
	v_add_u32_e32 v107, 0x83, v220
	v_lshl_add_u64 v[4:5], v[4:5], 0, v[142:143]
	global_store_dwordx4 v[4:5], v[30:33], off
	v_mad_i64_i32 v[4:5], s[0:1], v106, s4, v[2:3]
	v_mad_i64_i32 v[2:3], s[0:1], v107, s4, v[2:3]
	v_lshl_add_u64 v[4:5], v[4:5], 0, v[142:143]
	v_lshl_add_u64 v[2:3], v[2:3], 0, v[142:143]
	global_store_dwordx4 v[4:5], v[14:17], off
	global_store_dwordx4 v[2:3], v[10:13], off
	v_readlane_b32 s100, v254, 58
	s_mul_i32 s101, s100, 15
	v_cmp_eq_u32_e32 vcc, s101, v240
	s_and_saveexec_b64 s[98:99], vcc
	ds_read_b128 v[66:69], v208 offset:8192
	ds_read_b128 v[70:73], v208 offset:8256
	ds_read_b128 v[74:77], v208 offset:8320
	ds_read_b128 v[82:85], v208 offset:8384
	ds_read_b128 v[86:89], v208 offset:8448
	ds_read_b128 v[90:93], v208 offset:8512
	ds_read_b128 v[122:125], v208 offset:8576
	ds_read_b128 v[126:129], v208 offset:8640
	s_lshl_b32 s0, s10, 2
	s_lshl_b32 s100, s100, 1
	s_add_i32 s0, s0, s100
	s_mul_hi_i32 s7, s0, 0xb000
	s_mul_i32 s6, s0, 0xb000
	v_readlane_b32 s0, v252, 43
	v_readlane_b32 s1, v252, 44
	v_mov_b32_e32 v94, v209
	v_ashrrev_i32_e32 v95, 31, v94
	s_add_u32 s6, s0, s6
	s_addc_u32 s7, s1, s7
	v_lshlrev_b64 v[94:95], 2, v[94:95]
	v_lshl_add_u64 v[96:97], s[6:7], 0, v[94:95]
	s_add_u32 s6, s6, 0xb000
	s_addc_u32 s7, s7, 0
	v_lshl_add_u64 v[98:99], s[6:7], 0, v[94:95]
	s_waitcnt lgkmcnt(0)
	global_store_dwordx4 v[96:97], v[66:69], off
	global_store_dwordx4 v[96:97], v[70:73], off offset:16
	global_store_dwordx4 v[96:97], v[74:77], off offset:512
	global_store_dwordx4 v[96:97], v[82:85], off offset:528
	global_store_dwordx4 v[98:99], v[86:89], off
	global_store_dwordx4 v[98:99], v[90:93], off offset:16
	global_store_dwordx4 v[98:99], v[122:125], off offset:512
	global_store_dwordx4 v[98:99], v[126:129], off offset:528
	s_or_b64 exec, exec, s[98:99]
	v_readlane_b32 s0, v254, 42
	v_readlane_b32 s1, v254, 43
	s_andn2_b64 vcc, exec, s[0:1]
	s_mov_b64 s[0:1], -1
	s_cbranch_vccnz .LBB0_76
	s_and_b64 vcc, exec, s[8:9]
	s_cbranch_vccnz .LBB0_75
	s_barrier
	s_branch .LBB0_75

; __global__ void __launch_bounds__(NW * 64, 2) fwd_kernel(Args a) {
;     extern __shared__ __attribute__((aligned(16))) unsigned char lds_raw[];
	.amdhsa_kernel _Z10fwd_kernel4Args
		.amdhsa_group_segment_fixed_size 0
		.amdhsa_private_segment_fixed_size 0
		.amdhsa_kernarg_size 440
		.amdhsa_user_sgpr_count 2
		.amdhsa_user_sgpr_dispatch_ptr 0
		.amdhsa_user_sgpr_queue_ptr 0
		.amdhsa_user_sgpr_kernarg_segment_ptr 1
		.amdhsa_user_sgpr_dispatch_id 0
		.amdhsa_user_sgpr_kernarg_preload_length 0
		.amdhsa_user_sgpr_kernarg_preload_offset 0
		.amdhsa_user_sgpr_private_segment_size 0
		.amdhsa_uses_dynamic_stack 0
		.amdhsa_enable_private_segment 0
		.amdhsa_system_sgpr_workgroup_id_x 1
		.amdhsa_system_sgpr_workgroup_id_y 0
		.amdhsa_system_sgpr_workgroup_id_z 0
		.amdhsa_system_sgpr_workgroup_info 0
		.amdhsa_system_vgpr_workitem_id 2
		.amdhsa_next_free_vgpr 256
		.amdhsa_next_free_sgpr 102
		.amdhsa_accum_offset 256
		.amdhsa_reserve_vcc 1
		.amdhsa_float_round_mode_32 0
		.amdhsa_float_round_mode_16_64 0
		.amdhsa_float_denorm_mode_32 3
		.amdhsa_float_denorm_mode_16_64 3
		.amdhsa_dx10_clamp 1
		.amdhsa_ieee_mode 1
		.amdhsa_fp16_overflow 0
		.amdhsa_tg_split 0
		.amdhsa_exception_fp_ieee_invalid_op 0
		.amdhsa_exception_fp_denorm_src 0
		.amdhsa_exception_fp_ieee_div_zero 0
		.amdhsa_exception_fp_ieee_overflow 0
		.amdhsa_exception_fp_ieee_underflow 0
		.amdhsa_exception_fp_ieee_inexact 0
		.amdhsa_exception_int_div_zero 0
	.end_amdhsa_kernel

; __global__ void __launch_bounds__(NW * 64, 2) fwd_kernel(Args a) {
;     extern __shared__ __attribute__((aligned(16))) unsigned char lds_raw[];
amdhsa.kernels:
  - .agpr_count:     0
    .args:
      - .offset:         0
        .size:           184
        .value_kind:     by_value
      - .offset:         184
        .size:           4
        .value_kind:     hidden_block_count_x
      - .offset:         188
        .size:           4
        .value_kind:     hidden_block_count_y
      - .offset:         192
        .size:           4
        .value_kind:     hidden_block_count_z
      - .offset:         196
        .size:           2
        .value_kind:     hidden_group_size_x
      - .offset:         198
        .size:           2
        .value_kind:     hidden_group_size_y
      - .offset:         200
        .size:           2
        .value_kind:     hidden_group_size_z
      - .offset:         202
        .size:           2
        .value_kind:     hidden_remainder_x
      - .offset:         204
        .size:           2
        .value_kind:     hidden_remainder_y
      - .offset:         206
        .size:           2
        .value_kind:     hidden_remainder_z
      - .offset:         224
        .size:           8
        .value_kind:     hidden_global_offset_x
      - .offset:         232
        .size:           8
        .value_kind:     hidden_global_offset_y
      - .offset:         240
        .size:           8
        .value_kind:     hidden_global_offset_z
      - .offset:         248
        .size:           2
        .value_kind:     hidden_grid_dims
      - .offset:         272
        .size:           8
        .value_kind:     hidden_multigrid_sync_arg
      - .offset:         304
        .size:           4
        .value_kind:     hidden_dynamic_lds_size
    .group_segment_fixed_size: 0
    .kernarg_segment_align: 8
    .kernarg_segment_size: 440
    .language:       OpenCL C
    .language_version:
      - 2
      - 0
    .max_flat_workgroup_size: 512
    .name:           _Z10fwd_kernel4Args
    .private_segment_fixed_size: 0
    .sgpr_count:     108
    .sgpr_spill_count: 223
    .symbol:         _Z10fwd_kernel4Args.kd
    .uniform_work_group_size: 1
    .uses_dynamic_stack: false
    .vgpr_count:     256
    .vgpr_spill_count: 0
    .wavefront_size: 64
